# v47 + first K-loop iteration peeled with C=0 MFMAs (no accumulator zeroing moves)
# baseline (speedup 1.0000x reference)
.LBB0_141:
	s_ashr_i32 s47, s46, 31
	s_lshl_b64 s[36:37], s[46:47], 19
	s_add_u32 s48, s20, s36
	s_addc_u32 s49, s34, s37
	s_and_b64 s[36:37], s[42:43], exec
	s_cselect_b32 s47, s49, s17
	s_cselect_b32 s78, s48, s16
	s_ashr_i32 s15, s14, 31
	s_lshl_b64 s[36:37], s[14:15], 19
	s_add_u32 s50, s39, s36
	s_addc_u32 s51, s40, s37
	s_and_b64 s[36:37], s[42:43], exec
	s_cselect_b32 s15, s51, s19
	s_cselect_b32 s79, s50, s18
	s_add_u32 s16, s16, 0x40080
	s_addc_u32 s17, s17, 0
	s_add_u32 s83, s18, 0x100
	s_addc_u32 s85, s19, 0
	s_mov_b32 s88, -2
	v_readfirstlane_b32 s98, v208
	s_bitcmp1_b32 s98, 8
	s_cbranch_scc0 .Lsp_142
	s_setprio 1
.Lsp_142:
	s_add_u32 s18, s16, 0xfffc0080
	s_addc_u32 s19, s17, -1
	s_add_i32 s28, 0, 0x10000
	s_cmp_eq_u32 s88, 12
	s_cselect_b32 s53, s47, s19
	s_cselect_b32 s52, s78, s18
	v_add_u32_e32 v140, s28, v143
	s_cselect_b32 s19, s15, s85
	s_cselect_b32 s18, s79, s83
	s_add_i32 s29, 0, 0x14000
	ds_read_b128 v[146:149], v140
	ds_read_b128 v[150:153], v140 offset:1024
	ds_read_b128 v[154:157], v140 offset:2048
	ds_read_b128 v[158:161], v140 offset:3072
	v_add_u32_e32 v140, s29, v143
	ds_read_b128 v[162:165], v140
	ds_read_b128 v[166:169], v140 offset:1024
	ds_read_b128 v[174:177], v140 offset:2048
	ds_read_b128 v[178:181], v140 offset:3072
	v_lshl_add_u64 v[140:141], s[16:17], 0, v[136:137]
	s_add_i32 m0, s54, 0xc000
	ds_read_b128 v[182:185], v145
	ds_read_b128 v[186:189], v145 offset:1024
	ds_read_b128 v[190:193], v145 offset:2048
	ds_read_b128 v[194:197], v145 offset:3072
	ds_read_b128 v[198:201], v145 offset:4096
	ds_read_b128 v[202:205], v145 offset:5120
	ds_read_b128 v[236:239], v145 offset:6144
	ds_read_b128 v[240:243], v145 offset:7168
	global_load_lds_dwordx4 v[140:141], off
	v_lshl_add_u64 v[140:141], s[16:17], 0, v[138:139]
	s_add_i32 m0, s54, 0xe000
	s_nop 0
	global_load_lds_dwordx4 v[140:141], off
	s_waitcnt vmcnt(8)
	s_waitcnt lgkmcnt(0)
	s_barrier
	s_waitcnt lgkmcnt(0)
	v_mfma_f32_16x16x32_bf16 v[126:129], v[146:149], v[182:185], 0
	v_mfma_f32_16x16x32_bf16 v[118:121], v[154:157], v[182:185], 0
	v_mfma_f32_16x16x32_bf16 v[110:113], v[146:149], v[190:193], 0
	v_mfma_f32_16x16x32_bf16 v[102:105], v[154:157], v[190:193], 0
	v_mfma_f32_16x16x32_bf16 v[94:97], v[146:149], v[198:201], 0
	v_mfma_f32_16x16x32_bf16 v[86:89], v[154:157], v[198:201], 0
	v_mfma_f32_16x16x32_bf16 v[78:81], v[146:149], v[236:239], 0
	v_mfma_f32_16x16x32_bf16 v[70:73], v[154:157], v[236:239], 0
	v_mfma_f32_16x16x32_bf16 v[126:129], v[150:153], v[186:189], v[126:129]
	v_mfma_f32_16x16x32_bf16 v[118:121], v[158:161], v[186:189], v[118:121]
	v_mfma_f32_16x16x32_bf16 v[110:113], v[150:153], v[194:197], v[110:113]
	v_mfma_f32_16x16x32_bf16 v[102:105], v[158:161], v[194:197], v[102:105]
	v_mfma_f32_16x16x32_bf16 v[94:97], v[150:153], v[202:205], v[94:97]
	v_mfma_f32_16x16x32_bf16 v[86:89], v[158:161], v[202:205], v[86:89]
	v_mfma_f32_16x16x32_bf16 v[78:81], v[150:153], v[240:243], v[78:81]
	v_mfma_f32_16x16x32_bf16 v[70:73], v[158:161], v[240:243], v[70:73]
	v_mfma_f32_16x16x32_bf16 v[122:125], v[162:165], v[182:185], 0
	v_mfma_f32_16x16x32_bf16 v[114:117], v[174:177], v[182:185], 0
	v_mfma_f32_16x16x32_bf16 v[106:109], v[162:165], v[190:193], 0
	v_mfma_f32_16x16x32_bf16 v[98:101], v[174:177], v[190:193], 0
	v_mfma_f32_16x16x32_bf16 v[90:93], v[162:165], v[198:201], 0
	v_mfma_f32_16x16x32_bf16 v[82:85], v[174:177], v[198:201], 0
	v_mfma_f32_16x16x32_bf16 v[74:77], v[162:165], v[236:239], 0
	v_mfma_f32_16x16x32_bf16 v[66:69], v[174:177], v[236:239], 0
	v_mfma_f32_16x16x32_bf16 v[122:125], v[166:169], v[186:189], v[122:125]
	v_mfma_f32_16x16x32_bf16 v[114:117], v[178:181], v[186:189], v[114:117]
	v_mfma_f32_16x16x32_bf16 v[106:109], v[166:169], v[194:197], v[106:109]
	v_mfma_f32_16x16x32_bf16 v[98:101], v[178:181], v[194:197], v[98:101]
	v_mfma_f32_16x16x32_bf16 v[90:93], v[166:169], v[202:205], v[90:93]
	v_mfma_f32_16x16x32_bf16 v[82:85], v[178:181], v[202:205], v[82:85]
	v_mfma_f32_16x16x32_bf16 v[74:77], v[166:169], v[240:243], v[74:77]
	v_mfma_f32_16x16x32_bf16 v[66:69], v[178:181], v[240:243], v[66:69]
	s_barrier
	s_add_i32 s28, s28, s41
	v_lshl_add_u64 v[140:141], s[18:19], 0, v[0:1]
	s_mov_b32 m0, s28
	ds_read_b128 v[182:185], v145 offset:16384
	ds_read_b128 v[186:189], v145 offset:17408
	ds_read_b128 v[190:193], v145 offset:18432
	ds_read_b128 v[194:197], v145 offset:19456
	ds_read_b128 v[198:201], v145 offset:20480
	ds_read_b128 v[202:205], v145 offset:21504
	ds_read_b128 v[236:239], v145 offset:22528
	ds_read_b128 v[240:243], v145 offset:23552
	global_load_lds_dwordx4 v[140:141], off
	s_add_i32 m0, s28, 0x2000
	s_add_u32 s36, s18, 0x40000
	v_lshl_add_u64 v[206:207], s[18:19], 0, v[130:131]
	s_addc_u32 s37, s19, 0
	s_add_i32 s28, s29, s41
	global_load_lds_dwordx4 v[206:207], off
	v_lshl_add_u64 v[228:229], s[36:37], 0, v[0:1]
	s_mov_b32 m0, s28
	v_lshl_add_u64 v[244:245], s[52:53], 0, v[132:133]
	global_load_lds_dwordx4 v[228:229], off
	v_lshl_add_u64 v[228:229], s[36:37], 0, v[130:131]
	s_add_i32 m0, s28, 0x2000
	s_nop 0
	global_load_lds_dwordx4 v[228:229], off
	v_lshl_add_u64 v[228:229], s[52:53], 0, v[134:135]
	s_mov_b32 m0, s54
	s_nop 0
	global_load_lds_dwordx4 v[228:229], off
	s_mov_b32 m0, s55
	s_nop 0
	global_load_lds_dwordx4 v[244:245], off
	s_waitcnt vmcnt(8)
	s_waitcnt lgkmcnt(0)
	s_barrier
	s_waitcnt lgkmcnt(0)
	v_mfma_f32_16x16x32_bf16 v[62:65], v[146:149], v[182:185], 0
	v_mfma_f32_16x16x32_bf16 v[54:57], v[154:157], v[182:185], 0
	v_mfma_f32_16x16x32_bf16 v[46:49], v[146:149], v[190:193], 0
	v_mfma_f32_16x16x32_bf16 v[38:41], v[154:157], v[190:193], 0
	v_mfma_f32_16x16x32_bf16 v[30:33], v[146:149], v[198:201], 0
	v_mfma_f32_16x16x32_bf16 v[22:25], v[154:157], v[198:201], 0
	v_mfma_f32_16x16x32_bf16 v[14:17], v[146:149], v[236:239], 0
	v_mfma_f32_16x16x32_bf16 v[6:9], v[154:157], v[236:239], 0
	v_mfma_f32_16x16x32_bf16 v[62:65], v[150:153], v[186:189], v[62:65]
	v_mfma_f32_16x16x32_bf16 v[54:57], v[158:161], v[186:189], v[54:57]
	v_mfma_f32_16x16x32_bf16 v[46:49], v[150:153], v[194:197], v[46:49]
	v_mfma_f32_16x16x32_bf16 v[38:41], v[158:161], v[194:197], v[38:41]
	v_mfma_f32_16x16x32_bf16 v[30:33], v[150:153], v[202:205], v[30:33]
	v_mfma_f32_16x16x32_bf16 v[22:25], v[158:161], v[202:205], v[22:25]
	v_mfma_f32_16x16x32_bf16 v[14:17], v[150:153], v[240:243], v[14:17]
	v_mfma_f32_16x16x32_bf16 v[6:9], v[158:161], v[240:243], v[6:9]
	v_mfma_f32_16x16x32_bf16 v[58:61], v[162:165], v[182:185], 0
	v_mfma_f32_16x16x32_bf16 v[50:53], v[174:177], v[182:185], 0
	v_mfma_f32_16x16x32_bf16 v[42:45], v[162:165], v[190:193], 0
	v_mfma_f32_16x16x32_bf16 v[34:37], v[174:177], v[190:193], 0
	v_mfma_f32_16x16x32_bf16 v[26:29], v[162:165], v[198:201], 0
	v_mfma_f32_16x16x32_bf16 v[18:21], v[174:177], v[198:201], 0
	v_mfma_f32_16x16x32_bf16 v[10:13], v[162:165], v[236:239], 0
	v_mfma_f32_16x16x32_bf16 v[2:5], v[174:177], v[236:239], 0
	v_mfma_f32_16x16x32_bf16 v[58:61], v[166:169], v[186:189], v[58:61]
	v_mfma_f32_16x16x32_bf16 v[50:53], v[178:181], v[186:189], v[50:53]
	v_mfma_f32_16x16x32_bf16 v[42:45], v[166:169], v[194:197], v[42:45]
	v_mfma_f32_16x16x32_bf16 v[34:37], v[178:181], v[194:197], v[34:37]
	v_mfma_f32_16x16x32_bf16 v[26:29], v[166:169], v[202:205], v[26:29]
	v_mfma_f32_16x16x32_bf16 v[18:21], v[178:181], v[202:205], v[18:21]
	v_mfma_f32_16x16x32_bf16 v[10:13], v[166:169], v[240:243], v[10:13]
	v_mfma_f32_16x16x32_bf16 v[2:5], v[178:181], v[240:243], v[2:5]
	s_barrier
	s_add_i32 s28, 0, 0x18000
	s_add_i32 s29, 0, 0x1c000
	v_add_u32_e32 v158, s28, v143
	v_add_u32_e32 v178, s29, v143
	ds_read_b128 v[146:149], v158
	ds_read_b128 v[150:153], v158 offset:1024
	ds_read_b128 v[154:157], v158 offset:2048
	ds_read_b128 v[158:161], v158 offset:3072
	ds_read_b128 v[162:165], v178
	ds_read_b128 v[166:169], v178 offset:1024
	ds_read_b128 v[174:177], v178 offset:2048
	ds_read_b128 v[178:181], v178 offset:3072
	s_add_u32 s36, s52, 0x40000
	s_addc_u32 s37, s53, 0
	s_mov_b32 m0, s70
	v_lshl_add_u64 v[246:247], s[36:37], 0, v[134:135]
	ds_read_b128 v[182:185], v145 offset:32768
	ds_read_b128 v[186:189], v145 offset:33792
	ds_read_b128 v[190:193], v145 offset:34816
	ds_read_b128 v[194:197], v145 offset:35840
	ds_read_b128 v[198:201], v145 offset:36864
	ds_read_b128 v[202:205], v145 offset:37888
	ds_read_b128 v[236:239], v145 offset:38912
	ds_read_b128 v[240:243], v145 offset:39936
	global_load_lds_dwordx4 v[246:247], off
	v_lshl_add_u64 v[246:247], s[36:37], 0, v[132:133]
	s_mov_b32 m0, s71
	s_nop 0
	global_load_lds_dwordx4 v[246:247], off
	s_waitcnt vmcnt(8)
	s_waitcnt lgkmcnt(0)
	s_barrier
	s_waitcnt lgkmcnt(0)
	v_mfma_f32_16x16x32_bf16 v[126:129], v[146:149], v[182:185], v[126:129]
	v_mfma_f32_16x16x32_bf16 v[118:121], v[154:157], v[182:185], v[118:121]
	v_mfma_f32_16x16x32_bf16 v[110:113], v[146:149], v[190:193], v[110:113]
	v_mfma_f32_16x16x32_bf16 v[102:105], v[154:157], v[190:193], v[102:105]
	v_mfma_f32_16x16x32_bf16 v[94:97], v[146:149], v[198:201], v[94:97]
	v_mfma_f32_16x16x32_bf16 v[86:89], v[154:157], v[198:201], v[86:89]
	v_mfma_f32_16x16x32_bf16 v[78:81], v[146:149], v[236:239], v[78:81]
	v_mfma_f32_16x16x32_bf16 v[70:73], v[154:157], v[236:239], v[70:73]
	v_mfma_f32_16x16x32_bf16 v[126:129], v[150:153], v[186:189], v[126:129]
	v_mfma_f32_16x16x32_bf16 v[118:121], v[158:161], v[186:189], v[118:121]
	v_mfma_f32_16x16x32_bf16 v[110:113], v[150:153], v[194:197], v[110:113]
	v_mfma_f32_16x16x32_bf16 v[102:105], v[158:161], v[194:197], v[102:105]
	v_mfma_f32_16x16x32_bf16 v[94:97], v[150:153], v[202:205], v[94:97]
	v_mfma_f32_16x16x32_bf16 v[86:89], v[158:161], v[202:205], v[86:89]
	v_mfma_f32_16x16x32_bf16 v[78:81], v[150:153], v[240:243], v[78:81]
	v_mfma_f32_16x16x32_bf16 v[70:73], v[158:161], v[240:243], v[70:73]
	v_mfma_f32_16x16x32_bf16 v[122:125], v[162:165], v[182:185], v[122:125]
	v_mfma_f32_16x16x32_bf16 v[114:117], v[174:177], v[182:185], v[114:117]
	v_mfma_f32_16x16x32_bf16 v[106:109], v[162:165], v[190:193], v[106:109]
	v_mfma_f32_16x16x32_bf16 v[98:101], v[174:177], v[190:193], v[98:101]
	v_mfma_f32_16x16x32_bf16 v[90:93], v[162:165], v[198:201], v[90:93]
	v_mfma_f32_16x16x32_bf16 v[82:85], v[174:177], v[198:201], v[82:85]
	v_mfma_f32_16x16x32_bf16 v[74:77], v[162:165], v[236:239], v[74:77]
	v_mfma_f32_16x16x32_bf16 v[66:69], v[174:177], v[236:239], v[66:69]
	v_mfma_f32_16x16x32_bf16 v[122:125], v[166:169], v[186:189], v[122:125]
	v_mfma_f32_16x16x32_bf16 v[114:117], v[178:181], v[186:189], v[114:117]
	v_mfma_f32_16x16x32_bf16 v[106:109], v[166:169], v[194:197], v[106:109]
	v_mfma_f32_16x16x32_bf16 v[98:101], v[178:181], v[194:197], v[98:101]
	v_mfma_f32_16x16x32_bf16 v[90:93], v[166:169], v[202:205], v[90:93]
	v_mfma_f32_16x16x32_bf16 v[82:85], v[178:181], v[202:205], v[82:85]
	v_mfma_f32_16x16x32_bf16 v[74:77], v[166:169], v[240:243], v[74:77]
	v_mfma_f32_16x16x32_bf16 v[66:69], v[178:181], v[240:243], v[66:69]
	s_barrier
	s_add_i32 s28, s28, s41
	v_lshl_add_u64 v[140:141], v[140:141], 0, s[4:5]
	s_mov_b32 m0, s28
	ds_read_b128 v[182:185], v145 offset:49152
	ds_read_b128 v[186:189], v145 offset:50176
	ds_read_b128 v[190:193], v145 offset:51200
	ds_read_b128 v[194:197], v145 offset:52224
	ds_read_b128 v[198:201], v145 offset:53248
	ds_read_b128 v[202:205], v145 offset:54272
	ds_read_b128 v[236:239], v145 offset:55296
	ds_read_b128 v[240:243], v145 offset:56320
	global_load_lds_dwordx4 v[140:141], off
	s_add_i32 m0, s28, 0x2000
	s_add_u32 s18, s18, 0x40080
	v_lshl_add_u64 v[140:141], v[206:207], 0, s[4:5]
	s_addc_u32 s19, s19, 0
	s_add_i32 s28, s29, s41
	global_load_lds_dwordx4 v[140:141], off
	v_lshl_add_u64 v[140:141], s[18:19], 0, v[0:1]
	s_mov_b32 m0, s28
	s_nop 0
	global_load_lds_dwordx4 v[140:141], off
	v_lshl_add_u64 v[140:141], s[18:19], 0, v[130:131]
	s_add_i32 m0, s28, 0x2000
	s_nop 0
	global_load_lds_dwordx4 v[140:141], off
	v_lshl_add_u64 v[140:141], v[228:229], 0, s[4:5]
	s_mov_b32 m0, s74
	s_nop 0
	global_load_lds_dwordx4 v[140:141], off
	v_lshl_add_u64 v[140:141], v[244:245], 0, s[4:5]
	s_mov_b32 m0, s75
	s_nop 0
	global_load_lds_dwordx4 v[140:141], off
	s_waitcnt vmcnt(8)
	s_waitcnt lgkmcnt(0)
	s_barrier
	s_waitcnt lgkmcnt(0)
	v_mfma_f32_16x16x32_bf16 v[62:65], v[146:149], v[182:185], v[62:65]
	v_mfma_f32_16x16x32_bf16 v[54:57], v[154:157], v[182:185], v[54:57]
	v_mfma_f32_16x16x32_bf16 v[46:49], v[146:149], v[190:193], v[46:49]
	v_mfma_f32_16x16x32_bf16 v[38:41], v[154:157], v[190:193], v[38:41]
	v_mfma_f32_16x16x32_bf16 v[30:33], v[146:149], v[198:201], v[30:33]
	v_mfma_f32_16x16x32_bf16 v[22:25], v[154:157], v[198:201], v[22:25]
	v_mfma_f32_16x16x32_bf16 v[14:17], v[146:149], v[236:239], v[14:17]
	v_mfma_f32_16x16x32_bf16 v[6:9], v[154:157], v[236:239], v[6:9]
	v_mfma_f32_16x16x32_bf16 v[62:65], v[150:153], v[186:189], v[62:65]
	v_mfma_f32_16x16x32_bf16 v[54:57], v[158:161], v[186:189], v[54:57]
	v_mfma_f32_16x16x32_bf16 v[46:49], v[150:153], v[194:197], v[46:49]
	v_mfma_f32_16x16x32_bf16 v[38:41], v[158:161], v[194:197], v[38:41]
	v_mfma_f32_16x16x32_bf16 v[30:33], v[150:153], v[202:205], v[30:33]
	v_mfma_f32_16x16x32_bf16 v[22:25], v[158:161], v[202:205], v[22:25]
	v_mfma_f32_16x16x32_bf16 v[14:17], v[150:153], v[240:243], v[14:17]
	v_mfma_f32_16x16x32_bf16 v[6:9], v[158:161], v[240:243], v[6:9]
	v_mfma_f32_16x16x32_bf16 v[58:61], v[162:165], v[182:185], v[58:61]
	v_mfma_f32_16x16x32_bf16 v[50:53], v[174:177], v[182:185], v[50:53]
	v_mfma_f32_16x16x32_bf16 v[42:45], v[162:165], v[190:193], v[42:45]
	v_mfma_f32_16x16x32_bf16 v[34:37], v[174:177], v[190:193], v[34:37]
	v_mfma_f32_16x16x32_bf16 v[26:29], v[162:165], v[198:201], v[26:29]
	v_mfma_f32_16x16x32_bf16 v[18:21], v[174:177], v[198:201], v[18:21]
	v_mfma_f32_16x16x32_bf16 v[10:13], v[162:165], v[236:239], v[10:13]
	v_mfma_f32_16x16x32_bf16 v[2:5], v[174:177], v[236:239], v[2:5]
	v_mfma_f32_16x16x32_bf16 v[58:61], v[166:169], v[186:189], v[58:61]
	v_mfma_f32_16x16x32_bf16 v[50:53], v[178:181], v[186:189], v[50:53]
	v_mfma_f32_16x16x32_bf16 v[42:45], v[166:169], v[194:197], v[42:45]
	v_mfma_f32_16x16x32_bf16 v[34:37], v[178:181], v[194:197], v[34:37]
	v_mfma_f32_16x16x32_bf16 v[26:29], v[166:169], v[202:205], v[26:29]
	v_mfma_f32_16x16x32_bf16 v[18:21], v[178:181], v[202:205], v[18:21]
	v_mfma_f32_16x16x32_bf16 v[10:13], v[166:169], v[240:243], v[10:13]
	v_mfma_f32_16x16x32_bf16 v[2:5], v[178:181], v[240:243], v[2:5]
	s_barrier
	s_add_i32 s88, s88, 2
	s_add_u32 s16, s16, 0x100
	s_addc_u32 s17, s17, 0
	s_add_u32 s83, s83, 0x100
	s_addc_u32 s85, s85, 0
	s_cmp_gt_u32 s88, 13
	s_cbranch_scc1 .Lpeel_exit_142

.Lpeel_exit_142:
	s_setprio 0
	s_and_b64 vcc, exec, s[12:13]
	s_cbranch_vccz .LBB0_145
	s_barrier

.LBB0_193:
	s_add_u32 s10, s10, 0x80
	s_addc_u32 s11, s11, 0
	s_add_u32 s14, s12, 0x100
	s_addc_u32 s15, s13, 0
	s_mov_b32 s12, 0
	s_waitcnt vmcnt(0)
	v_readfirstlane_b32 s98, v208
	s_bitcmp1_b32 s98, 8
	s_cbranch_scc0 .Lsp_194
	s_setprio 1
.Lsp_194:
	s_add_i32 vcc_lo, s12, 2
	s_add_u32 s36, s10, 0x80
	s_addc_u32 s13, s11, 0
	s_add_i32 vcc_hi, 0, 0x10000
	s_cmp_eq_u32 s94, s12
	s_cselect_b32 s13, s45, s13
	s_cselect_b32 s12, s44, s36
	s_cselect_b32 s37, s79, s15
	s_cselect_b32 s36, s78, s14
	s_add_i32 s8, 0, 0x14000
	v_add_u32_e32 v126, vcc_hi, v197
	v_add_u32_e32 v158, s8, v197
	ds_read_b128 v[114:117], v126
	ds_read_b128 v[118:121], v126 offset:1024
	ds_read_b128 v[122:125], v126 offset:2048
	ds_read_b128 v[126:129], v126 offset:3072
	ds_read_b128 v[146:149], v158
	ds_read_b128 v[150:153], v158 offset:1024
	ds_read_b128 v[154:157], v158 offset:2048
	ds_read_b128 v[158:161], v158 offset:3072
	v_lshl_add_u64 v[240:241], s[10:11], 0, v[180:181]
	s_add_i32 m0, s18, 0xc000
	ds_read_b128 v[162:165], v199
	ds_read_b128 v[166:169], v199 offset:1024
	ds_read_b128 v[184:187], v199 offset:2048
	ds_read_b128 v[188:191], v199 offset:3072
	ds_read_b128 v[192:195], v199 offset:4096
	ds_read_b128 v[200:203], v199 offset:5120
	ds_read_b128 v[204:207], v199 offset:6144
	ds_read_b128 v[236:239], v199 offset:7168
	global_load_lds_dwordx4 v[240:241], off
	v_lshl_add_u64 v[240:241], s[10:11], 0, v[182:183]
	s_add_i32 m0, s18, 0xe000
	s_nop 0
	global_load_lds_dwordx4 v[240:241], off
	s_waitcnt vmcnt(8)
	s_waitcnt lgkmcnt(0)
	s_barrier
	s_waitcnt lgkmcnt(0)
	v_mfma_f32_16x16x32_bf16 v[142:145], v[114:117], v[162:165], 0
	v_mfma_f32_16x16x32_bf16 v[138:141], v[122:125], v[162:165], 0
	v_mfma_f32_16x16x32_bf16 v[110:113], v[114:117], v[184:187], 0
	v_mfma_f32_16x16x32_bf16 v[106:109], v[122:125], v[184:187], 0
	v_mfma_f32_16x16x32_bf16 v[94:97], v[114:117], v[192:195], 0
	v_mfma_f32_16x16x32_bf16 v[90:93], v[122:125], v[192:195], 0
	v_mfma_f32_16x16x32_bf16 v[78:81], v[114:117], v[204:207], 0
	v_mfma_f32_16x16x32_bf16 v[74:77], v[122:125], v[204:207], 0
	v_mfma_f32_16x16x32_bf16 v[142:145], v[118:121], v[166:169], v[142:145]
	v_mfma_f32_16x16x32_bf16 v[138:141], v[126:129], v[166:169], v[138:141]
	v_mfma_f32_16x16x32_bf16 v[110:113], v[118:121], v[188:191], v[110:113]
	v_mfma_f32_16x16x32_bf16 v[106:109], v[126:129], v[188:191], v[106:109]
	v_mfma_f32_16x16x32_bf16 v[94:97], v[118:121], v[200:203], v[94:97]
	v_mfma_f32_16x16x32_bf16 v[90:93], v[126:129], v[200:203], v[90:93]
	v_mfma_f32_16x16x32_bf16 v[78:81], v[118:121], v[236:239], v[78:81]
	v_mfma_f32_16x16x32_bf16 v[74:77], v[126:129], v[236:239], v[74:77]
	v_mfma_f32_16x16x32_bf16 v[134:137], v[146:149], v[162:165], 0
	v_mfma_f32_16x16x32_bf16 v[130:133], v[154:157], v[162:165], 0
	v_mfma_f32_16x16x32_bf16 v[102:105], v[146:149], v[184:187], 0
	v_mfma_f32_16x16x32_bf16 v[98:101], v[154:157], v[184:187], 0
	v_mfma_f32_16x16x32_bf16 v[86:89], v[146:149], v[192:195], 0
	v_mfma_f32_16x16x32_bf16 v[82:85], v[154:157], v[192:195], 0
	v_mfma_f32_16x16x32_bf16 v[70:73], v[146:149], v[204:207], 0
	v_mfma_f32_16x16x32_bf16 v[66:69], v[154:157], v[204:207], 0
	v_mfma_f32_16x16x32_bf16 v[134:137], v[150:153], v[166:169], v[134:137]
	v_mfma_f32_16x16x32_bf16 v[130:133], v[158:161], v[166:169], v[130:133]
	v_mfma_f32_16x16x32_bf16 v[102:105], v[150:153], v[188:191], v[102:105]
	v_mfma_f32_16x16x32_bf16 v[98:101], v[158:161], v[188:191], v[98:101]
	v_mfma_f32_16x16x32_bf16 v[86:89], v[150:153], v[200:203], v[86:89]
	v_mfma_f32_16x16x32_bf16 v[82:85], v[158:161], v[200:203], v[82:85]
	v_mfma_f32_16x16x32_bf16 v[70:73], v[150:153], v[236:239], v[70:73]
	v_mfma_f32_16x16x32_bf16 v[66:69], v[158:161], v[236:239], v[66:69]
	s_barrier
	s_add_i32 s9, vcc_hi, s17
	v_lshl_add_u64 v[240:241], s[36:37], 0, v[0:1]
	s_mov_b32 m0, s9
	ds_read_b128 v[162:165], v199 offset:16384
	ds_read_b128 v[166:169], v199 offset:17408
	ds_read_b128 v[184:187], v199 offset:18432
	ds_read_b128 v[188:191], v199 offset:19456
	ds_read_b128 v[192:195], v199 offset:20480
	ds_read_b128 v[200:203], v199 offset:21504
	ds_read_b128 v[204:207], v199 offset:22528
	ds_read_b128 v[236:239], v199 offset:23552
	global_load_lds_dwordx4 v[240:241], off
	s_add_i32 m0, s9, 0x2000
	v_lshl_add_u64 v[242:243], s[36:37], 0, v[174:175]
	s_add_u32 s36, s36, s20
	s_addc_u32 s37, s37, 0
	s_add_i32 s8, s8, s17
	global_load_lds_dwordx4 v[242:243], off
	v_lshl_add_u64 v[244:245], s[36:37], 0, v[0:1]
	s_mov_b32 m0, s8
	v_lshl_add_u64 v[246:247], s[36:37], 0, v[174:175]
	global_load_lds_dwordx4 v[244:245], off
	s_add_i32 m0, s8, 0x2000
	v_lshl_add_u64 v[248:249], s[12:13], 0, v[178:179]
	global_load_lds_dwordx4 v[246:247], off
	s_mov_b32 m0, s18
	v_lshl_add_u64 v[250:251], s[12:13], 0, v[176:177]
	global_load_lds_dwordx4 v[248:249], off
	s_mov_b32 m0, s19
	s_nop 0
	global_load_lds_dwordx4 v[250:251], off
	s_waitcnt vmcnt(8)
	s_waitcnt lgkmcnt(0)
	s_barrier
	s_waitcnt lgkmcnt(0)
	v_mfma_f32_16x16x32_bf16 v[62:65], v[114:117], v[162:165], 0
	v_mfma_f32_16x16x32_bf16 v[58:61], v[122:125], v[162:165], 0
	v_mfma_f32_16x16x32_bf16 v[46:49], v[114:117], v[184:187], 0
	v_mfma_f32_16x16x32_bf16 v[42:45], v[122:125], v[184:187], 0
	v_mfma_f32_16x16x32_bf16 v[30:33], v[114:117], v[192:195], 0
	v_mfma_f32_16x16x32_bf16 v[26:29], v[122:125], v[192:195], 0
	v_mfma_f32_16x16x32_bf16 v[14:17], v[114:117], v[204:207], 0
	v_mfma_f32_16x16x32_bf16 v[10:13], v[122:125], v[204:207], 0
	v_mfma_f32_16x16x32_bf16 v[62:65], v[118:121], v[166:169], v[62:65]
	v_mfma_f32_16x16x32_bf16 v[58:61], v[126:129], v[166:169], v[58:61]
	v_mfma_f32_16x16x32_bf16 v[46:49], v[118:121], v[188:191], v[46:49]
	v_mfma_f32_16x16x32_bf16 v[42:45], v[126:129], v[188:191], v[42:45]
	v_mfma_f32_16x16x32_bf16 v[30:33], v[118:121], v[200:203], v[30:33]
	v_mfma_f32_16x16x32_bf16 v[26:29], v[126:129], v[200:203], v[26:29]
	v_mfma_f32_16x16x32_bf16 v[14:17], v[118:121], v[236:239], v[14:17]
	v_mfma_f32_16x16x32_bf16 v[10:13], v[126:129], v[236:239], v[10:13]
	v_mfma_f32_16x16x32_bf16 v[54:57], v[146:149], v[162:165], 0
	v_mfma_f32_16x16x32_bf16 v[50:53], v[154:157], v[162:165], 0
	v_mfma_f32_16x16x32_bf16 v[38:41], v[146:149], v[184:187], 0
	v_mfma_f32_16x16x32_bf16 v[34:37], v[154:157], v[184:187], 0
	v_mfma_f32_16x16x32_bf16 v[22:25], v[146:149], v[192:195], 0
	v_mfma_f32_16x16x32_bf16 v[18:21], v[154:157], v[192:195], 0
	v_mfma_f32_16x16x32_bf16 v[6:9], v[146:149], v[204:207], 0
	v_mfma_f32_16x16x32_bf16 v[2:5], v[154:157], v[204:207], 0
	v_mfma_f32_16x16x32_bf16 v[54:57], v[150:153], v[166:169], v[54:57]
	v_mfma_f32_16x16x32_bf16 v[50:53], v[158:161], v[166:169], v[50:53]
	v_mfma_f32_16x16x32_bf16 v[38:41], v[150:153], v[188:191], v[38:41]
	v_mfma_f32_16x16x32_bf16 v[34:37], v[158:161], v[188:191], v[34:37]
	v_mfma_f32_16x16x32_bf16 v[22:25], v[150:153], v[200:203], v[22:25]
	v_mfma_f32_16x16x32_bf16 v[18:21], v[158:161], v[200:203], v[18:21]
	v_mfma_f32_16x16x32_bf16 v[6:9], v[150:153], v[236:239], v[6:9]
	v_mfma_f32_16x16x32_bf16 v[2:5], v[158:161], v[236:239], v[2:5]
	s_barrier
	s_add_i32 s8, 0, 0x18000
	s_add_i32 s9, 0, 0x1c000
	v_add_u32_e32 v126, s8, v197
	v_add_u32_e32 v158, s9, v197
	ds_read_b128 v[114:117], v126
	ds_read_b128 v[118:121], v126 offset:1024
	ds_read_b128 v[122:125], v126 offset:2048
	ds_read_b128 v[126:129], v126 offset:3072
	ds_read_b128 v[146:149], v158
	ds_read_b128 v[150:153], v158 offset:1024
	ds_read_b128 v[154:157], v158 offset:2048
	ds_read_b128 v[158:161], v158 offset:3072
	s_add_u32 s12, s12, s20
	s_addc_u32 s13, s13, 0
	s_mov_b32 m0, s70
	v_lshl_add_u64 v[228:229], s[12:13], 0, v[178:179]
	ds_read_b128 v[162:165], v199 offset:32768
	ds_read_b128 v[166:169], v199 offset:33792
	ds_read_b128 v[184:187], v199 offset:34816
	ds_read_b128 v[188:191], v199 offset:35840
	ds_read_b128 v[192:195], v199 offset:36864
	ds_read_b128 v[200:203], v199 offset:37888
	ds_read_b128 v[204:207], v199 offset:38912
	ds_read_b128 v[236:239], v199 offset:39936
	global_load_lds_dwordx4 v[228:229], off
	v_lshl_add_u64 v[228:229], s[12:13], 0, v[176:177]
	s_mov_b32 m0, s71
	s_nop 0
	global_load_lds_dwordx4 v[228:229], off
	s_waitcnt vmcnt(8)
	s_waitcnt lgkmcnt(0)
	s_barrier
	s_waitcnt lgkmcnt(0)
	v_mfma_f32_16x16x32_bf16 v[142:145], v[114:117], v[162:165], v[142:145]
	v_mfma_f32_16x16x32_bf16 v[138:141], v[122:125], v[162:165], v[138:141]
	v_mfma_f32_16x16x32_bf16 v[110:113], v[114:117], v[184:187], v[110:113]
	v_mfma_f32_16x16x32_bf16 v[106:109], v[122:125], v[184:187], v[106:109]
	v_mfma_f32_16x16x32_bf16 v[94:97], v[114:117], v[192:195], v[94:97]
	v_mfma_f32_16x16x32_bf16 v[90:93], v[122:125], v[192:195], v[90:93]
	v_mfma_f32_16x16x32_bf16 v[78:81], v[114:117], v[204:207], v[78:81]
	v_mfma_f32_16x16x32_bf16 v[74:77], v[122:125], v[204:207], v[74:77]
	v_mfma_f32_16x16x32_bf16 v[142:145], v[118:121], v[166:169], v[142:145]
	v_mfma_f32_16x16x32_bf16 v[138:141], v[126:129], v[166:169], v[138:141]
	v_mfma_f32_16x16x32_bf16 v[110:113], v[118:121], v[188:191], v[110:113]
	v_mfma_f32_16x16x32_bf16 v[106:109], v[126:129], v[188:191], v[106:109]
	v_mfma_f32_16x16x32_bf16 v[94:97], v[118:121], v[200:203], v[94:97]
	v_mfma_f32_16x16x32_bf16 v[90:93], v[126:129], v[200:203], v[90:93]
	v_mfma_f32_16x16x32_bf16 v[78:81], v[118:121], v[236:239], v[78:81]
	v_mfma_f32_16x16x32_bf16 v[74:77], v[126:129], v[236:239], v[74:77]
	v_mfma_f32_16x16x32_bf16 v[134:137], v[146:149], v[162:165], v[134:137]
	v_mfma_f32_16x16x32_bf16 v[130:133], v[154:157], v[162:165], v[130:133]
	v_mfma_f32_16x16x32_bf16 v[102:105], v[146:149], v[184:187], v[102:105]
	v_mfma_f32_16x16x32_bf16 v[98:101], v[154:157], v[184:187], v[98:101]
	v_mfma_f32_16x16x32_bf16 v[86:89], v[146:149], v[192:195], v[86:89]
	v_mfma_f32_16x16x32_bf16 v[82:85], v[154:157], v[192:195], v[82:85]
	v_mfma_f32_16x16x32_bf16 v[70:73], v[146:149], v[204:207], v[70:73]
	v_mfma_f32_16x16x32_bf16 v[66:69], v[154:157], v[204:207], v[66:69]
	v_mfma_f32_16x16x32_bf16 v[134:137], v[150:153], v[166:169], v[134:137]
	v_mfma_f32_16x16x32_bf16 v[130:133], v[158:161], v[166:169], v[130:133]
	v_mfma_f32_16x16x32_bf16 v[102:105], v[150:153], v[188:191], v[102:105]
	v_mfma_f32_16x16x32_bf16 v[98:101], v[158:161], v[188:191], v[98:101]
	v_mfma_f32_16x16x32_bf16 v[86:89], v[150:153], v[200:203], v[86:89]
	v_mfma_f32_16x16x32_bf16 v[82:85], v[158:161], v[200:203], v[82:85]
	v_mfma_f32_16x16x32_bf16 v[70:73], v[150:153], v[236:239], v[70:73]
	v_mfma_f32_16x16x32_bf16 v[66:69], v[158:161], v[236:239], v[66:69]
	s_barrier
	s_add_i32 s8, s8, s17
	v_lshl_add_u64 v[228:229], v[240:241], 0, s[4:5]
	s_mov_b32 m0, s8
	ds_read_b128 v[162:165], v199 offset:49152
	ds_read_b128 v[166:169], v199 offset:50176
	ds_read_b128 v[184:187], v199 offset:51200
	ds_read_b128 v[188:191], v199 offset:52224
	ds_read_b128 v[192:195], v199 offset:53248
	ds_read_b128 v[200:203], v199 offset:54272
	ds_read_b128 v[204:207], v199 offset:55296
	ds_read_b128 v[236:239], v199 offset:56320
	global_load_lds_dwordx4 v[228:229], off
	v_lshl_add_u64 v[228:229], v[242:243], 0, s[4:5]
	s_add_i32 m0, s8, 0x2000
	s_add_i32 s8, s9, s17
	global_load_lds_dwordx4 v[228:229], off
	v_lshl_add_u64 v[228:229], v[244:245], 0, s[4:5]
	s_mov_b32 m0, s8
	s_nop 0
	global_load_lds_dwordx4 v[228:229], off
	v_lshl_add_u64 v[228:229], v[246:247], 0, s[4:5]
	s_add_i32 m0, s8, 0x2000
	s_nop 0
	global_load_lds_dwordx4 v[228:229], off
	v_lshl_add_u64 v[228:229], v[248:249], 0, s[4:5]
	s_mov_b32 m0, s88
	s_nop 0
	global_load_lds_dwordx4 v[228:229], off
	v_lshl_add_u64 v[228:229], v[250:251], 0, s[4:5]
	s_mov_b32 m0, s89
	s_nop 0
	global_load_lds_dwordx4 v[228:229], off
	s_waitcnt vmcnt(8)
	s_waitcnt lgkmcnt(0)
	s_barrier
	s_waitcnt lgkmcnt(0)
	v_mfma_f32_16x16x32_bf16 v[62:65], v[114:117], v[162:165], v[62:65]
	v_mfma_f32_16x16x32_bf16 v[58:61], v[122:125], v[162:165], v[58:61]
	v_mfma_f32_16x16x32_bf16 v[46:49], v[114:117], v[184:187], v[46:49]
	v_mfma_f32_16x16x32_bf16 v[42:45], v[122:125], v[184:187], v[42:45]
	v_mfma_f32_16x16x32_bf16 v[30:33], v[114:117], v[192:195], v[30:33]
	v_mfma_f32_16x16x32_bf16 v[26:29], v[122:125], v[192:195], v[26:29]
	v_mfma_f32_16x16x32_bf16 v[14:17], v[114:117], v[204:207], v[14:17]
	v_mfma_f32_16x16x32_bf16 v[10:13], v[122:125], v[204:207], v[10:13]
	v_mfma_f32_16x16x32_bf16 v[62:65], v[118:121], v[166:169], v[62:65]
	v_mfma_f32_16x16x32_bf16 v[58:61], v[126:129], v[166:169], v[58:61]
	v_mfma_f32_16x16x32_bf16 v[46:49], v[118:121], v[188:191], v[46:49]
	v_mfma_f32_16x16x32_bf16 v[42:45], v[126:129], v[188:191], v[42:45]
	v_mfma_f32_16x16x32_bf16 v[30:33], v[118:121], v[200:203], v[30:33]
	v_mfma_f32_16x16x32_bf16 v[26:29], v[126:129], v[200:203], v[26:29]
	v_mfma_f32_16x16x32_bf16 v[14:17], v[118:121], v[236:239], v[14:17]
	v_mfma_f32_16x16x32_bf16 v[10:13], v[126:129], v[236:239], v[10:13]
	v_mfma_f32_16x16x32_bf16 v[54:57], v[146:149], v[162:165], v[54:57]
	v_mfma_f32_16x16x32_bf16 v[50:53], v[154:157], v[162:165], v[50:53]
	v_mfma_f32_16x16x32_bf16 v[38:41], v[146:149], v[184:187], v[38:41]
	v_mfma_f32_16x16x32_bf16 v[34:37], v[154:157], v[184:187], v[34:37]
	v_mfma_f32_16x16x32_bf16 v[22:25], v[146:149], v[192:195], v[22:25]
	v_mfma_f32_16x16x32_bf16 v[18:21], v[154:157], v[192:195], v[18:21]
	v_mfma_f32_16x16x32_bf16 v[6:9], v[146:149], v[204:207], v[6:9]
	v_mfma_f32_16x16x32_bf16 v[2:5], v[154:157], v[204:207], v[2:5]
	v_mfma_f32_16x16x32_bf16 v[54:57], v[150:153], v[166:169], v[54:57]
	v_mfma_f32_16x16x32_bf16 v[50:53], v[158:161], v[166:169], v[50:53]
	v_mfma_f32_16x16x32_bf16 v[38:41], v[150:153], v[188:191], v[38:41]
	v_mfma_f32_16x16x32_bf16 v[34:37], v[158:161], v[188:191], v[34:37]
	v_mfma_f32_16x16x32_bf16 v[22:25], v[150:153], v[200:203], v[22:25]
	v_mfma_f32_16x16x32_bf16 v[18:21], v[158:161], v[200:203], v[18:21]
	v_mfma_f32_16x16x32_bf16 v[6:9], v[150:153], v[236:239], v[6:9]
	v_mfma_f32_16x16x32_bf16 v[2:5], v[158:161], v[236:239], v[2:5]
	s_barrier
	s_add_u32 s10, s10, 0x100
	s_addc_u32 s11, s11, 0
	s_add_u32 s14, s14, 0x100
	s_addc_u32 s15, s15, 0
	s_cmp_ge_u32 vcc_lo, s77
	s_mov_b32 s12, vcc_lo
	s_cbranch_scc1 .Lpeel_exit_194

.Lpeel_exit_194:
	s_setprio 0
	s_and_b64 vcc, exec, s[54:55]
	s_cbranch_vccz .LBB0_197
	s_barrier

.LBB0_218:
	s_add_u32 s18, s18, 0x80
	s_addc_u32 s19, s19, 0
	s_add_u32 s11, s48, 0x100
	s_addc_u32 s15, s49, 0
	s_mov_b32 s48, 0
	v_readfirstlane_b32 s98, v208
	s_bitcmp1_b32 s98, 8
	s_cbranch_scc0 .Lsp_219
	s_setprio 1
.Lsp_219:
	s_add_i32 vcc_lo, s48, 2
	s_add_u32 s36, s18, 0x80
	s_addc_u32 s37, s19, 0
	s_add_i32 vcc_hi, 0, 0x10000
	s_cmp_eq_u32 s89, s48
	s_cselect_b32 s49, s17, s37
	s_cselect_b32 s48, s16, s36
	s_cselect_b32 s37, s45, s15
	s_cselect_b32 s36, s44, s11
	s_add_i32 s28, 0, 0x14000
	v_add_u32_e32 v156, vcc_hi, v141
	v_add_u32_e32 v168, s28, v141
	ds_read_b128 v[144:147], v156
	ds_read_b128 v[148:151], v156 offset:1024
	ds_read_b128 v[152:155], v156 offset:2048
	ds_read_b128 v[156:159], v156 offset:3072
	ds_read_b128 v[160:163], v168
	ds_read_b128 v[164:167], v168 offset:1024
	ds_read_b128 v[174:177], v168 offset:2048
	ds_read_b128 v[178:181], v168 offset:3072
	v_lshl_add_u64 v[168:169], s[18:19], 0, v[136:137]
	s_add_i32 m0, s54, 0xc000
	ds_read_b128 v[182:185], v143
	ds_read_b128 v[186:189], v143 offset:1024
	ds_read_b128 v[190:193], v143 offset:2048
	ds_read_b128 v[194:197], v143 offset:3072
	ds_read_b128 v[198:201], v143 offset:4096
	ds_read_b128 v[202:205], v143 offset:5120
	ds_read_b128 v[236:239], v143 offset:6144
	ds_read_b128 v[240:243], v143 offset:7168
	global_load_lds_dwordx4 v[168:169], off
	v_lshl_add_u64 v[168:169], s[18:19], 0, v[138:139]
	s_add_i32 m0, s54, 0xe000
	s_nop 0
	global_load_lds_dwordx4 v[168:169], off
	s_waitcnt vmcnt(8)
	s_waitcnt lgkmcnt(0)
	s_barrier
	s_waitcnt lgkmcnt(0)
	v_mfma_f32_16x16x32_bf16 v[126:129], v[144:147], v[182:185], 0
	v_mfma_f32_16x16x32_bf16 v[122:125], v[152:155], v[182:185], 0
	v_mfma_f32_16x16x32_bf16 v[118:121], v[144:147], v[190:193], 0
	v_mfma_f32_16x16x32_bf16 v[114:117], v[152:155], v[190:193], 0
	v_mfma_f32_16x16x32_bf16 v[106:109], v[144:147], v[198:201], 0
	v_mfma_f32_16x16x32_bf16 v[98:101], v[152:155], v[198:201], 0
	v_mfma_f32_16x16x32_bf16 v[90:93], v[144:147], v[236:239], 0
	v_mfma_f32_16x16x32_bf16 v[82:85], v[152:155], v[236:239], 0
	v_mfma_f32_16x16x32_bf16 v[126:129], v[148:151], v[186:189], v[126:129]
	v_mfma_f32_16x16x32_bf16 v[122:125], v[156:159], v[186:189], v[122:125]
	v_mfma_f32_16x16x32_bf16 v[118:121], v[148:151], v[194:197], v[118:121]
	v_mfma_f32_16x16x32_bf16 v[114:117], v[156:159], v[194:197], v[114:117]
	v_mfma_f32_16x16x32_bf16 v[106:109], v[148:151], v[202:205], v[106:109]
	v_mfma_f32_16x16x32_bf16 v[98:101], v[156:159], v[202:205], v[98:101]
	v_mfma_f32_16x16x32_bf16 v[90:93], v[148:151], v[240:243], v[90:93]
	v_mfma_f32_16x16x32_bf16 v[82:85], v[156:159], v[240:243], v[82:85]
	v_mfma_f32_16x16x32_bf16 v[110:113], v[160:163], v[182:185], 0
	v_mfma_f32_16x16x32_bf16 v[102:105], v[174:177], v[182:185], 0
	v_mfma_f32_16x16x32_bf16 v[94:97], v[160:163], v[190:193], 0
	v_mfma_f32_16x16x32_bf16 v[86:89], v[174:177], v[190:193], 0
	v_mfma_f32_16x16x32_bf16 v[78:81], v[160:163], v[198:201], 0
	v_mfma_f32_16x16x32_bf16 v[74:77], v[174:177], v[198:201], 0
	v_mfma_f32_16x16x32_bf16 v[70:73], v[160:163], v[236:239], 0
	v_mfma_f32_16x16x32_bf16 v[66:69], v[174:177], v[236:239], 0
	v_mfma_f32_16x16x32_bf16 v[110:113], v[164:167], v[186:189], v[110:113]
	v_mfma_f32_16x16x32_bf16 v[102:105], v[178:181], v[186:189], v[102:105]
	v_mfma_f32_16x16x32_bf16 v[94:97], v[164:167], v[194:197], v[94:97]
	v_mfma_f32_16x16x32_bf16 v[86:89], v[178:181], v[194:197], v[86:89]
	v_mfma_f32_16x16x32_bf16 v[78:81], v[164:167], v[202:205], v[78:81]
	v_mfma_f32_16x16x32_bf16 v[74:77], v[178:181], v[202:205], v[74:77]
	v_mfma_f32_16x16x32_bf16 v[70:73], v[164:167], v[240:243], v[70:73]
	v_mfma_f32_16x16x32_bf16 v[66:69], v[178:181], v[240:243], v[66:69]
	s_barrier
	s_add_i32 s29, vcc_hi, s41
	v_lshl_add_u64 v[168:169], s[36:37], 0, v[0:1]
	s_mov_b32 m0, s29
	ds_read_b128 v[182:185], v143 offset:16384
	ds_read_b128 v[186:189], v143 offset:17408
	ds_read_b128 v[190:193], v143 offset:18432
	ds_read_b128 v[194:197], v143 offset:19456
	ds_read_b128 v[198:201], v143 offset:20480
	ds_read_b128 v[202:205], v143 offset:21504
	ds_read_b128 v[236:239], v143 offset:22528
	ds_read_b128 v[240:243], v143 offset:23552
	global_load_lds_dwordx4 v[168:169], off
	s_add_i32 m0, s29, 0x2000
	v_lshl_add_u64 v[206:207], s[36:37], 0, v[130:131]
	s_add_u32 s36, s36, s20
	s_addc_u32 s37, s37, 0
	s_add_i32 s28, s28, s41
	global_load_lds_dwordx4 v[206:207], off
	v_lshl_add_u64 v[228:229], s[36:37], 0, v[0:1]
	s_mov_b32 m0, s28
	v_lshl_add_u64 v[244:245], s[36:37], 0, v[130:131]
	global_load_lds_dwordx4 v[228:229], off
	s_add_i32 m0, s28, 0x2000
	v_lshl_add_u64 v[246:247], s[48:49], 0, v[134:135]
	global_load_lds_dwordx4 v[244:245], off
	s_mov_b32 m0, s54
	v_lshl_add_u64 v[248:249], s[48:49], 0, v[132:133]
	global_load_lds_dwordx4 v[246:247], off
	s_mov_b32 m0, s55
	s_nop 0
	global_load_lds_dwordx4 v[248:249], off
	s_waitcnt vmcnt(8)
	s_waitcnt lgkmcnt(0)
	s_barrier
	s_waitcnt lgkmcnt(0)
	v_mfma_f32_16x16x32_bf16 v[62:65], v[144:147], v[182:185], 0
	v_mfma_f32_16x16x32_bf16 v[58:61], v[152:155], v[182:185], 0
	v_mfma_f32_16x16x32_bf16 v[54:57], v[144:147], v[190:193], 0
	v_mfma_f32_16x16x32_bf16 v[50:53], v[152:155], v[190:193], 0
	v_mfma_f32_16x16x32_bf16 v[42:45], v[144:147], v[198:201], 0
	v_mfma_f32_16x16x32_bf16 v[34:37], v[152:155], v[198:201], 0
	v_mfma_f32_16x16x32_bf16 v[26:29], v[144:147], v[236:239], 0
	v_mfma_f32_16x16x32_bf16 v[18:21], v[152:155], v[236:239], 0
	v_mfma_f32_16x16x32_bf16 v[62:65], v[148:151], v[186:189], v[62:65]
	v_mfma_f32_16x16x32_bf16 v[58:61], v[156:159], v[186:189], v[58:61]
	v_mfma_f32_16x16x32_bf16 v[54:57], v[148:151], v[194:197], v[54:57]
	v_mfma_f32_16x16x32_bf16 v[50:53], v[156:159], v[194:197], v[50:53]
	v_mfma_f32_16x16x32_bf16 v[42:45], v[148:151], v[202:205], v[42:45]
	v_mfma_f32_16x16x32_bf16 v[34:37], v[156:159], v[202:205], v[34:37]
	v_mfma_f32_16x16x32_bf16 v[26:29], v[148:151], v[240:243], v[26:29]
	v_mfma_f32_16x16x32_bf16 v[18:21], v[156:159], v[240:243], v[18:21]
	v_mfma_f32_16x16x32_bf16 v[46:49], v[160:163], v[182:185], 0
	v_mfma_f32_16x16x32_bf16 v[38:41], v[174:177], v[182:185], 0
	v_mfma_f32_16x16x32_bf16 v[30:33], v[160:163], v[190:193], 0
	v_mfma_f32_16x16x32_bf16 v[22:25], v[174:177], v[190:193], 0
	v_mfma_f32_16x16x32_bf16 v[14:17], v[160:163], v[198:201], 0
	v_mfma_f32_16x16x32_bf16 v[10:13], v[174:177], v[198:201], 0
	v_mfma_f32_16x16x32_bf16 v[6:9], v[160:163], v[236:239], 0
	v_mfma_f32_16x16x32_bf16 v[2:5], v[174:177], v[236:239], 0
	v_mfma_f32_16x16x32_bf16 v[46:49], v[164:167], v[186:189], v[46:49]
	v_mfma_f32_16x16x32_bf16 v[38:41], v[178:181], v[186:189], v[38:41]
	v_mfma_f32_16x16x32_bf16 v[30:33], v[164:167], v[194:197], v[30:33]
	v_mfma_f32_16x16x32_bf16 v[22:25], v[178:181], v[194:197], v[22:25]
	v_mfma_f32_16x16x32_bf16 v[14:17], v[164:167], v[202:205], v[14:17]
	v_mfma_f32_16x16x32_bf16 v[10:13], v[178:181], v[202:205], v[10:13]
	v_mfma_f32_16x16x32_bf16 v[6:9], v[164:167], v[240:243], v[6:9]
	v_mfma_f32_16x16x32_bf16 v[2:5], v[178:181], v[240:243], v[2:5]
	s_barrier
	s_add_i32 s28, 0, 0x18000
	s_add_i32 s29, 0, 0x1c000
	v_add_u32_e32 v156, s28, v141
	v_add_u32_e32 v178, s29, v141
	ds_read_b128 v[144:147], v156
	ds_read_b128 v[148:151], v156 offset:1024
	ds_read_b128 v[152:155], v156 offset:2048
	ds_read_b128 v[156:159], v156 offset:3072
	ds_read_b128 v[160:163], v178
	ds_read_b128 v[164:167], v178 offset:1024
	ds_read_b128 v[174:177], v178 offset:2048
	ds_read_b128 v[178:181], v178 offset:3072
	s_add_u32 s36, s48, s20
	s_addc_u32 s37, s49, 0
	s_mov_b32 m0, s70
	v_lshl_add_u64 v[250:251], s[36:37], 0, v[134:135]
	ds_read_b128 v[182:185], v143 offset:32768
	ds_read_b128 v[186:189], v143 offset:33792
	ds_read_b128 v[190:193], v143 offset:34816
	ds_read_b128 v[194:197], v143 offset:35840
	ds_read_b128 v[198:201], v143 offset:36864
	ds_read_b128 v[202:205], v143 offset:37888
	ds_read_b128 v[236:239], v143 offset:38912
	ds_read_b128 v[240:243], v143 offset:39936
	global_load_lds_dwordx4 v[250:251], off
	v_lshl_add_u64 v[250:251], s[36:37], 0, v[132:133]
	s_mov_b32 m0, s71
	s_nop 0
	global_load_lds_dwordx4 v[250:251], off
	s_waitcnt vmcnt(8)
	s_waitcnt lgkmcnt(0)
	s_barrier
	s_waitcnt lgkmcnt(0)
	v_mfma_f32_16x16x32_bf16 v[126:129], v[144:147], v[182:185], v[126:129]
	v_mfma_f32_16x16x32_bf16 v[122:125], v[152:155], v[182:185], v[122:125]
	v_mfma_f32_16x16x32_bf16 v[118:121], v[144:147], v[190:193], v[118:121]
	v_mfma_f32_16x16x32_bf16 v[114:117], v[152:155], v[190:193], v[114:117]
	v_mfma_f32_16x16x32_bf16 v[106:109], v[144:147], v[198:201], v[106:109]
	v_mfma_f32_16x16x32_bf16 v[98:101], v[152:155], v[198:201], v[98:101]
	v_mfma_f32_16x16x32_bf16 v[90:93], v[144:147], v[236:239], v[90:93]
	v_mfma_f32_16x16x32_bf16 v[82:85], v[152:155], v[236:239], v[82:85]
	v_mfma_f32_16x16x32_bf16 v[126:129], v[148:151], v[186:189], v[126:129]
	v_mfma_f32_16x16x32_bf16 v[122:125], v[156:159], v[186:189], v[122:125]
	v_mfma_f32_16x16x32_bf16 v[118:121], v[148:151], v[194:197], v[118:121]
	v_mfma_f32_16x16x32_bf16 v[114:117], v[156:159], v[194:197], v[114:117]
	v_mfma_f32_16x16x32_bf16 v[106:109], v[148:151], v[202:205], v[106:109]
	v_mfma_f32_16x16x32_bf16 v[98:101], v[156:159], v[202:205], v[98:101]
	v_mfma_f32_16x16x32_bf16 v[90:93], v[148:151], v[240:243], v[90:93]
	v_mfma_f32_16x16x32_bf16 v[82:85], v[156:159], v[240:243], v[82:85]
	v_mfma_f32_16x16x32_bf16 v[110:113], v[160:163], v[182:185], v[110:113]
	v_mfma_f32_16x16x32_bf16 v[102:105], v[174:177], v[182:185], v[102:105]
	v_mfma_f32_16x16x32_bf16 v[94:97], v[160:163], v[190:193], v[94:97]
	v_mfma_f32_16x16x32_bf16 v[86:89], v[174:177], v[190:193], v[86:89]
	v_mfma_f32_16x16x32_bf16 v[78:81], v[160:163], v[198:201], v[78:81]
	v_mfma_f32_16x16x32_bf16 v[74:77], v[174:177], v[198:201], v[74:77]
	v_mfma_f32_16x16x32_bf16 v[70:73], v[160:163], v[236:239], v[70:73]
	v_mfma_f32_16x16x32_bf16 v[66:69], v[174:177], v[236:239], v[66:69]
	v_mfma_f32_16x16x32_bf16 v[110:113], v[164:167], v[186:189], v[110:113]
	v_mfma_f32_16x16x32_bf16 v[102:105], v[178:181], v[186:189], v[102:105]
	v_mfma_f32_16x16x32_bf16 v[94:97], v[164:167], v[194:197], v[94:97]
	v_mfma_f32_16x16x32_bf16 v[86:89], v[178:181], v[194:197], v[86:89]
	v_mfma_f32_16x16x32_bf16 v[78:81], v[164:167], v[202:205], v[78:81]
	v_mfma_f32_16x16x32_bf16 v[74:77], v[178:181], v[202:205], v[74:77]
	v_mfma_f32_16x16x32_bf16 v[70:73], v[164:167], v[240:243], v[70:73]
	v_mfma_f32_16x16x32_bf16 v[66:69], v[178:181], v[240:243], v[66:69]
	s_barrier
	s_add_i32 s28, s28, s41
	v_lshl_add_u64 v[168:169], v[168:169], 0, s[4:5]
	s_mov_b32 m0, s28
	ds_read_b128 v[182:185], v143 offset:49152
	ds_read_b128 v[186:189], v143 offset:50176
	ds_read_b128 v[190:193], v143 offset:51200
	ds_read_b128 v[194:197], v143 offset:52224
	ds_read_b128 v[198:201], v143 offset:53248
	ds_read_b128 v[202:205], v143 offset:54272
	ds_read_b128 v[236:239], v143 offset:55296
	ds_read_b128 v[240:243], v143 offset:56320
	global_load_lds_dwordx4 v[168:169], off
	v_lshl_add_u64 v[168:169], v[206:207], 0, s[4:5]
	s_add_i32 m0, s28, 0x2000
	s_add_i32 s28, s29, s41
	global_load_lds_dwordx4 v[168:169], off
	v_lshl_add_u64 v[168:169], v[228:229], 0, s[4:5]
	s_mov_b32 m0, s28
	s_nop 0
	global_load_lds_dwordx4 v[168:169], off
	v_lshl_add_u64 v[168:169], v[244:245], 0, s[4:5]
	s_add_i32 m0, s28, 0x2000
	s_nop 0
	global_load_lds_dwordx4 v[168:169], off
	v_lshl_add_u64 v[168:169], v[246:247], 0, s[4:5]
	s_mov_b32 m0, s83
	s_nop 0
	global_load_lds_dwordx4 v[168:169], off
	v_lshl_add_u64 v[168:169], v[248:249], 0, s[4:5]
	s_mov_b32 m0, s85
	s_nop 0
	global_load_lds_dwordx4 v[168:169], off
	s_waitcnt vmcnt(8)
	s_waitcnt lgkmcnt(0)
	s_barrier
	s_waitcnt lgkmcnt(0)
	v_mfma_f32_16x16x32_bf16 v[62:65], v[144:147], v[182:185], v[62:65]
	v_mfma_f32_16x16x32_bf16 v[58:61], v[152:155], v[182:185], v[58:61]
	v_mfma_f32_16x16x32_bf16 v[54:57], v[144:147], v[190:193], v[54:57]
	v_mfma_f32_16x16x32_bf16 v[50:53], v[152:155], v[190:193], v[50:53]
	v_mfma_f32_16x16x32_bf16 v[42:45], v[144:147], v[198:201], v[42:45]
	v_mfma_f32_16x16x32_bf16 v[34:37], v[152:155], v[198:201], v[34:37]
	v_mfma_f32_16x16x32_bf16 v[26:29], v[144:147], v[236:239], v[26:29]
	v_mfma_f32_16x16x32_bf16 v[18:21], v[152:155], v[236:239], v[18:21]
	v_mfma_f32_16x16x32_bf16 v[62:65], v[148:151], v[186:189], v[62:65]
	v_mfma_f32_16x16x32_bf16 v[58:61], v[156:159], v[186:189], v[58:61]
	v_mfma_f32_16x16x32_bf16 v[54:57], v[148:151], v[194:197], v[54:57]
	v_mfma_f32_16x16x32_bf16 v[50:53], v[156:159], v[194:197], v[50:53]
	v_mfma_f32_16x16x32_bf16 v[42:45], v[148:151], v[202:205], v[42:45]
	v_mfma_f32_16x16x32_bf16 v[34:37], v[156:159], v[202:205], v[34:37]
	v_mfma_f32_16x16x32_bf16 v[26:29], v[148:151], v[240:243], v[26:29]
	v_mfma_f32_16x16x32_bf16 v[18:21], v[156:159], v[240:243], v[18:21]
	v_mfma_f32_16x16x32_bf16 v[46:49], v[160:163], v[182:185], v[46:49]
	v_mfma_f32_16x16x32_bf16 v[38:41], v[174:177], v[182:185], v[38:41]
	v_mfma_f32_16x16x32_bf16 v[30:33], v[160:163], v[190:193], v[30:33]
	v_mfma_f32_16x16x32_bf16 v[22:25], v[174:177], v[190:193], v[22:25]
	v_mfma_f32_16x16x32_bf16 v[14:17], v[160:163], v[198:201], v[14:17]
	v_mfma_f32_16x16x32_bf16 v[10:13], v[174:177], v[198:201], v[10:13]
	v_mfma_f32_16x16x32_bf16 v[6:9], v[160:163], v[236:239], v[6:9]
	v_mfma_f32_16x16x32_bf16 v[2:5], v[174:177], v[236:239], v[2:5]
	v_mfma_f32_16x16x32_bf16 v[46:49], v[164:167], v[186:189], v[46:49]
	v_mfma_f32_16x16x32_bf16 v[38:41], v[178:181], v[186:189], v[38:41]
	v_mfma_f32_16x16x32_bf16 v[30:33], v[164:167], v[194:197], v[30:33]
	v_mfma_f32_16x16x32_bf16 v[22:25], v[178:181], v[194:197], v[22:25]
	v_mfma_f32_16x16x32_bf16 v[14:17], v[164:167], v[202:205], v[14:17]
	v_mfma_f32_16x16x32_bf16 v[10:13], v[178:181], v[202:205], v[10:13]
	v_mfma_f32_16x16x32_bf16 v[6:9], v[164:167], v[240:243], v[6:9]
	v_mfma_f32_16x16x32_bf16 v[2:5], v[178:181], v[240:243], v[2:5]
	s_barrier
	s_add_u32 s18, s18, 0x100
	s_addc_u32 s19, s19, 0
	s_add_u32 s11, s11, 0x100
	s_addc_u32 s15, s15, 0
	s_cmp_ge_u32 vcc_lo, s79
	s_mov_b32 s48, vcc_lo
	s_cbranch_scc1 .Lpeel_exit_219

.Lpeel_exit_219:
	s_setprio 0
	s_and_b64 vcc, exec, s[8:9]
	s_cbranch_vccz .LBB0_222
	s_barrier

.LBB0_436:
	s_ashr_i32 s9, s8, 31
	s_lshl_b64 s[14:15], s[8:9], 19
	s_cmp_eq_u32 s75, 0
	s_cselect_b32 s36, s20, s16
	s_cselect_b32 s9, s39, s17
	s_cselect_b32 s37, s16, s20
	s_cselect_b32 s46, s17, s39
	s_add_u32 s50, s36, s14
	s_addc_u32 s51, s9, s15
	s_and_b64 s[14:15], s[42:43], exec
	s_cselect_b32 s9, s51, s11
	s_cselect_b32 s45, s50, s10
	s_waitcnt lgkmcnt(0)
	s_ashr_i32 s49, s48, 31
	s_lshl_b64 s[14:15], s[48:49], 19
	s_add_u32 s52, s37, s14
	s_addc_u32 s53, s46, s15
	s_and_b64 s[14:15], s[42:43], exec
	s_cselect_b32 s46, s53, s13
	s_cselect_b32 s47, s52, s12
	s_add_u32 s10, s10, 0x40080
	s_addc_u32 s11, s11, 0
	s_add_u32 s49, s12, 0x100
	s_addc_u32 s77, s13, 0
	s_mov_b32 s78, -2
	v_readfirstlane_b32 s98, v208
	s_bitcmp1_b32 s98, 8
	s_cbranch_scc0 .Lsp_437
	s_setprio 1
.Lsp_437:
	s_add_u32 s12, s10, 0xfffc0080
	s_addc_u32 s13, s11, -1
	s_add_i32 s36, 0, 0x10000
	s_cmp_eq_u32 s78, 12
	s_cselect_b32 s15, s9, s13
	s_cselect_b32 s14, s45, s12
	s_cselect_b32 s13, s46, s77
	s_cselect_b32 s12, s47, s49
	s_add_i32 s37, 0, 0x14000
	v_add_u32_e32 v156, s36, v145
	v_add_u32_e32 v168, s37, v145
	ds_read_b128 v[140:143], v156
	ds_read_b128 v[148:151], v156 offset:1024
	ds_read_b128 v[152:155], v156 offset:2048
	ds_read_b128 v[156:159], v156 offset:3072
	ds_read_b128 v[160:163], v168
	ds_read_b128 v[164:167], v168 offset:1024
	ds_read_b128 v[174:177], v168 offset:2048
	ds_read_b128 v[178:181], v168 offset:3072
	v_lshl_add_u64 v[168:169], s[10:11], 0, v[136:137]
	s_add_i32 m0, s19, 0xc000
	ds_read_b128 v[182:185], v147
	ds_read_b128 v[186:189], v147 offset:1024
	ds_read_b128 v[190:193], v147 offset:2048
	ds_read_b128 v[194:197], v147 offset:3072
	ds_read_b128 v[198:201], v147 offset:4096
	ds_read_b128 v[202:205], v147 offset:5120
	ds_read_b128 v[236:239], v147 offset:6144
	ds_read_b128 v[240:243], v147 offset:7168
	global_load_lds_dwordx4 v[168:169], off
	v_lshl_add_u64 v[168:169], s[10:11], 0, v[138:139]
	s_add_i32 m0, s19, 0xe000
	s_nop 0
	global_load_lds_dwordx4 v[168:169], off
	s_waitcnt vmcnt(8)
	s_waitcnt lgkmcnt(0)
	s_barrier
	s_waitcnt lgkmcnt(0)
	v_mfma_f32_16x16x32_bf16 v[126:129], v[140:143], v[182:185], 0
	v_mfma_f32_16x16x32_bf16 v[122:125], v[152:155], v[182:185], 0
	v_mfma_f32_16x16x32_bf16 v[110:113], v[140:143], v[190:193], 0
	v_mfma_f32_16x16x32_bf16 v[106:109], v[152:155], v[190:193], 0
	v_mfma_f32_16x16x32_bf16 v[94:97], v[140:143], v[198:201], 0
	v_mfma_f32_16x16x32_bf16 v[90:93], v[152:155], v[198:201], 0
	v_mfma_f32_16x16x32_bf16 v[78:81], v[140:143], v[236:239], 0
	v_mfma_f32_16x16x32_bf16 v[74:77], v[152:155], v[236:239], 0
	v_mfma_f32_16x16x32_bf16 v[126:129], v[148:151], v[186:189], v[126:129]
	v_mfma_f32_16x16x32_bf16 v[122:125], v[156:159], v[186:189], v[122:125]
	v_mfma_f32_16x16x32_bf16 v[110:113], v[148:151], v[194:197], v[110:113]
	v_mfma_f32_16x16x32_bf16 v[106:109], v[156:159], v[194:197], v[106:109]
	v_mfma_f32_16x16x32_bf16 v[94:97], v[148:151], v[202:205], v[94:97]
	v_mfma_f32_16x16x32_bf16 v[90:93], v[156:159], v[202:205], v[90:93]
	v_mfma_f32_16x16x32_bf16 v[78:81], v[148:151], v[240:243], v[78:81]
	v_mfma_f32_16x16x32_bf16 v[74:77], v[156:159], v[240:243], v[74:77]
	v_mfma_f32_16x16x32_bf16 v[118:121], v[160:163], v[182:185], 0
	v_mfma_f32_16x16x32_bf16 v[114:117], v[174:177], v[182:185], 0
	v_mfma_f32_16x16x32_bf16 v[102:105], v[160:163], v[190:193], 0
	v_mfma_f32_16x16x32_bf16 v[98:101], v[174:177], v[190:193], 0
	v_mfma_f32_16x16x32_bf16 v[86:89], v[160:163], v[198:201], 0
	v_mfma_f32_16x16x32_bf16 v[82:85], v[174:177], v[198:201], 0
	v_mfma_f32_16x16x32_bf16 v[70:73], v[160:163], v[236:239], 0
	v_mfma_f32_16x16x32_bf16 v[66:69], v[174:177], v[236:239], 0
	v_mfma_f32_16x16x32_bf16 v[118:121], v[164:167], v[186:189], v[118:121]
	v_mfma_f32_16x16x32_bf16 v[114:117], v[178:181], v[186:189], v[114:117]
	v_mfma_f32_16x16x32_bf16 v[102:105], v[164:167], v[194:197], v[102:105]
	v_mfma_f32_16x16x32_bf16 v[98:101], v[178:181], v[194:197], v[98:101]
	v_mfma_f32_16x16x32_bf16 v[86:89], v[164:167], v[202:205], v[86:89]
	v_mfma_f32_16x16x32_bf16 v[82:85], v[178:181], v[202:205], v[82:85]
	v_mfma_f32_16x16x32_bf16 v[70:73], v[164:167], v[240:243], v[70:73]
	v_mfma_f32_16x16x32_bf16 v[66:69], v[178:181], v[240:243], v[66:69]
	s_barrier
	s_add_i32 s36, s36, s18
	v_lshl_add_u64 v[168:169], s[12:13], 0, v[0:1]
	s_mov_b32 m0, s36
	ds_read_b128 v[182:185], v147 offset:16384
	ds_read_b128 v[186:189], v147 offset:17408
	ds_read_b128 v[190:193], v147 offset:18432
	ds_read_b128 v[194:197], v147 offset:19456
	ds_read_b128 v[198:201], v147 offset:20480
	ds_read_b128 v[202:205], v147 offset:21504
	ds_read_b128 v[236:239], v147 offset:22528
	ds_read_b128 v[240:243], v147 offset:23552
	global_load_lds_dwordx4 v[168:169], off
	s_add_i32 m0, s36, 0x2000
	s_add_u32 s82, s12, 0x40000
	v_lshl_add_u64 v[206:207], s[12:13], 0, v[130:131]
	s_addc_u32 s83, s13, 0
	s_add_i32 s36, s37, s18
	global_load_lds_dwordx4 v[206:207], off
	v_lshl_add_u64 v[244:245], s[82:83], 0, v[0:1]
	s_mov_b32 m0, s36
	v_lshl_add_u64 v[246:247], s[14:15], 0, v[132:133]
	global_load_lds_dwordx4 v[244:245], off
	v_lshl_add_u64 v[244:245], s[82:83], 0, v[130:131]
	s_add_i32 m0, s36, 0x2000
	s_nop 0
	global_load_lds_dwordx4 v[244:245], off
	v_lshl_add_u64 v[244:245], s[14:15], 0, v[134:135]
	s_mov_b32 m0, s19
	s_nop 0
	global_load_lds_dwordx4 v[244:245], off
	s_mov_b32 m0, s34
	s_nop 0
	global_load_lds_dwordx4 v[246:247], off
	s_waitcnt vmcnt(8)
	s_waitcnt lgkmcnt(0)
	s_barrier
	s_waitcnt lgkmcnt(0)
	v_mfma_f32_16x16x32_bf16 v[62:65], v[140:143], v[182:185], 0
	v_mfma_f32_16x16x32_bf16 v[58:61], v[152:155], v[182:185], 0
	v_mfma_f32_16x16x32_bf16 v[46:49], v[140:143], v[190:193], 0
	v_mfma_f32_16x16x32_bf16 v[42:45], v[152:155], v[190:193], 0
	v_mfma_f32_16x16x32_bf16 v[30:33], v[140:143], v[198:201], 0
	v_mfma_f32_16x16x32_bf16 v[26:29], v[152:155], v[198:201], 0
	v_mfma_f32_16x16x32_bf16 v[14:17], v[140:143], v[236:239], 0
	v_mfma_f32_16x16x32_bf16 v[10:13], v[152:155], v[236:239], 0
	v_mfma_f32_16x16x32_bf16 v[62:65], v[148:151], v[186:189], v[62:65]
	v_mfma_f32_16x16x32_bf16 v[58:61], v[156:159], v[186:189], v[58:61]
	v_mfma_f32_16x16x32_bf16 v[46:49], v[148:151], v[194:197], v[46:49]
	v_mfma_f32_16x16x32_bf16 v[42:45], v[156:159], v[194:197], v[42:45]
	v_mfma_f32_16x16x32_bf16 v[30:33], v[148:151], v[202:205], v[30:33]
	v_mfma_f32_16x16x32_bf16 v[26:29], v[156:159], v[202:205], v[26:29]
	v_mfma_f32_16x16x32_bf16 v[14:17], v[148:151], v[240:243], v[14:17]
	v_mfma_f32_16x16x32_bf16 v[10:13], v[156:159], v[240:243], v[10:13]
	v_mfma_f32_16x16x32_bf16 v[54:57], v[160:163], v[182:185], 0
	v_mfma_f32_16x16x32_bf16 v[50:53], v[174:177], v[182:185], 0
	v_mfma_f32_16x16x32_bf16 v[38:41], v[160:163], v[190:193], 0
	v_mfma_f32_16x16x32_bf16 v[34:37], v[174:177], v[190:193], 0
	v_mfma_f32_16x16x32_bf16 v[22:25], v[160:163], v[198:201], 0
	v_mfma_f32_16x16x32_bf16 v[18:21], v[174:177], v[198:201], 0
	v_mfma_f32_16x16x32_bf16 v[6:9], v[160:163], v[236:239], 0
	v_mfma_f32_16x16x32_bf16 v[2:5], v[174:177], v[236:239], 0
	v_mfma_f32_16x16x32_bf16 v[54:57], v[164:167], v[186:189], v[54:57]
	v_mfma_f32_16x16x32_bf16 v[50:53], v[178:181], v[186:189], v[50:53]
	v_mfma_f32_16x16x32_bf16 v[38:41], v[164:167], v[194:197], v[38:41]
	v_mfma_f32_16x16x32_bf16 v[34:37], v[178:181], v[194:197], v[34:37]
	v_mfma_f32_16x16x32_bf16 v[22:25], v[164:167], v[202:205], v[22:25]
	v_mfma_f32_16x16x32_bf16 v[18:21], v[178:181], v[202:205], v[18:21]
	v_mfma_f32_16x16x32_bf16 v[6:9], v[164:167], v[240:243], v[6:9]
	v_mfma_f32_16x16x32_bf16 v[2:5], v[178:181], v[240:243], v[2:5]
	s_barrier
	s_add_i32 s36, 0, 0x18000
	s_add_i32 s37, 0, 0x1c000
	v_add_u32_e32 v156, s36, v145
	v_add_u32_e32 v178, s37, v145
	ds_read_b128 v[140:143], v156
	ds_read_b128 v[148:151], v156 offset:1024
	ds_read_b128 v[152:155], v156 offset:2048
	ds_read_b128 v[156:159], v156 offset:3072
	ds_read_b128 v[160:163], v178
	ds_read_b128 v[164:167], v178 offset:1024
	ds_read_b128 v[174:177], v178 offset:2048
	ds_read_b128 v[178:181], v178 offset:3072
	s_add_u32 s14, s14, 0x40000
	s_addc_u32 s15, s15, 0
	s_mov_b32 m0, s54
	v_lshl_add_u64 v[248:249], s[14:15], 0, v[134:135]
	ds_read_b128 v[182:185], v147 offset:32768
	ds_read_b128 v[186:189], v147 offset:33792
	ds_read_b128 v[190:193], v147 offset:34816
	ds_read_b128 v[194:197], v147 offset:35840
	ds_read_b128 v[198:201], v147 offset:36864
	ds_read_b128 v[202:205], v147 offset:37888
	ds_read_b128 v[236:239], v147 offset:38912
	ds_read_b128 v[240:243], v147 offset:39936
	global_load_lds_dwordx4 v[248:249], off
	v_lshl_add_u64 v[248:249], s[14:15], 0, v[132:133]
	s_mov_b32 m0, s55
	s_nop 0
	global_load_lds_dwordx4 v[248:249], off
	s_waitcnt vmcnt(8)
	s_waitcnt lgkmcnt(0)
	s_barrier
	s_waitcnt lgkmcnt(0)
	v_mfma_f32_16x16x32_bf16 v[126:129], v[140:143], v[182:185], v[126:129]
	v_mfma_f32_16x16x32_bf16 v[122:125], v[152:155], v[182:185], v[122:125]
	v_mfma_f32_16x16x32_bf16 v[110:113], v[140:143], v[190:193], v[110:113]
	v_mfma_f32_16x16x32_bf16 v[106:109], v[152:155], v[190:193], v[106:109]
	v_mfma_f32_16x16x32_bf16 v[94:97], v[140:143], v[198:201], v[94:97]
	v_mfma_f32_16x16x32_bf16 v[90:93], v[152:155], v[198:201], v[90:93]
	v_mfma_f32_16x16x32_bf16 v[78:81], v[140:143], v[236:239], v[78:81]
	v_mfma_f32_16x16x32_bf16 v[74:77], v[152:155], v[236:239], v[74:77]
	v_mfma_f32_16x16x32_bf16 v[126:129], v[148:151], v[186:189], v[126:129]
	v_mfma_f32_16x16x32_bf16 v[122:125], v[156:159], v[186:189], v[122:125]
	v_mfma_f32_16x16x32_bf16 v[110:113], v[148:151], v[194:197], v[110:113]
	v_mfma_f32_16x16x32_bf16 v[106:109], v[156:159], v[194:197], v[106:109]
	v_mfma_f32_16x16x32_bf16 v[94:97], v[148:151], v[202:205], v[94:97]
	v_mfma_f32_16x16x32_bf16 v[90:93], v[156:159], v[202:205], v[90:93]
	v_mfma_f32_16x16x32_bf16 v[78:81], v[148:151], v[240:243], v[78:81]
	v_mfma_f32_16x16x32_bf16 v[74:77], v[156:159], v[240:243], v[74:77]
	v_mfma_f32_16x16x32_bf16 v[118:121], v[160:163], v[182:185], v[118:121]
	v_mfma_f32_16x16x32_bf16 v[114:117], v[174:177], v[182:185], v[114:117]
	v_mfma_f32_16x16x32_bf16 v[102:105], v[160:163], v[190:193], v[102:105]
	v_mfma_f32_16x16x32_bf16 v[98:101], v[174:177], v[190:193], v[98:101]
	v_mfma_f32_16x16x32_bf16 v[86:89], v[160:163], v[198:201], v[86:89]
	v_mfma_f32_16x16x32_bf16 v[82:85], v[174:177], v[198:201], v[82:85]
	v_mfma_f32_16x16x32_bf16 v[70:73], v[160:163], v[236:239], v[70:73]
	v_mfma_f32_16x16x32_bf16 v[66:69], v[174:177], v[236:239], v[66:69]
	v_mfma_f32_16x16x32_bf16 v[118:121], v[164:167], v[186:189], v[118:121]
	v_mfma_f32_16x16x32_bf16 v[114:117], v[178:181], v[186:189], v[114:117]
	v_mfma_f32_16x16x32_bf16 v[102:105], v[164:167], v[194:197], v[102:105]
	v_mfma_f32_16x16x32_bf16 v[98:101], v[178:181], v[194:197], v[98:101]
	v_mfma_f32_16x16x32_bf16 v[86:89], v[164:167], v[202:205], v[86:89]
	v_mfma_f32_16x16x32_bf16 v[82:85], v[178:181], v[202:205], v[82:85]
	v_mfma_f32_16x16x32_bf16 v[70:73], v[164:167], v[240:243], v[70:73]
	v_mfma_f32_16x16x32_bf16 v[66:69], v[178:181], v[240:243], v[66:69]
	s_barrier
	s_add_i32 s14, s36, s18
	v_lshl_add_u64 v[168:169], v[168:169], 0, s[4:5]
	s_mov_b32 m0, s14
	ds_read_b128 v[182:185], v147 offset:49152
	ds_read_b128 v[186:189], v147 offset:50176
	ds_read_b128 v[190:193], v147 offset:51200
	ds_read_b128 v[194:197], v147 offset:52224
	ds_read_b128 v[198:201], v147 offset:53248
	ds_read_b128 v[202:205], v147 offset:54272
	ds_read_b128 v[236:239], v147 offset:55296
	ds_read_b128 v[240:243], v147 offset:56320
	global_load_lds_dwordx4 v[168:169], off
	s_add_i32 m0, s14, 0x2000
	s_add_u32 s12, s12, 0x40080
	v_lshl_add_u64 v[168:169], v[206:207], 0, s[4:5]
	s_addc_u32 s13, s13, 0
	s_add_i32 s14, s37, s18
	global_load_lds_dwordx4 v[168:169], off
	v_lshl_add_u64 v[168:169], s[12:13], 0, v[0:1]
	s_mov_b32 m0, s14
	s_nop 0
	global_load_lds_dwordx4 v[168:169], off
	v_lshl_add_u64 v[168:169], s[12:13], 0, v[130:131]
	s_add_i32 m0, s14, 0x2000
	s_nop 0
	global_load_lds_dwordx4 v[168:169], off
	v_lshl_add_u64 v[168:169], v[244:245], 0, s[4:5]
	s_mov_b32 m0, s70
	s_nop 0
	global_load_lds_dwordx4 v[168:169], off
	v_lshl_add_u64 v[168:169], v[246:247], 0, s[4:5]
	s_mov_b32 m0, s71
	s_nop 0
	global_load_lds_dwordx4 v[168:169], off
	s_waitcnt vmcnt(8)
	s_waitcnt lgkmcnt(0)
	s_barrier
	s_waitcnt lgkmcnt(0)
	v_mfma_f32_16x16x32_bf16 v[62:65], v[140:143], v[182:185], v[62:65]
	v_mfma_f32_16x16x32_bf16 v[58:61], v[152:155], v[182:185], v[58:61]
	v_mfma_f32_16x16x32_bf16 v[46:49], v[140:143], v[190:193], v[46:49]
	v_mfma_f32_16x16x32_bf16 v[42:45], v[152:155], v[190:193], v[42:45]
	v_mfma_f32_16x16x32_bf16 v[30:33], v[140:143], v[198:201], v[30:33]
	v_mfma_f32_16x16x32_bf16 v[26:29], v[152:155], v[198:201], v[26:29]
	v_mfma_f32_16x16x32_bf16 v[14:17], v[140:143], v[236:239], v[14:17]
	v_mfma_f32_16x16x32_bf16 v[10:13], v[152:155], v[236:239], v[10:13]
	v_mfma_f32_16x16x32_bf16 v[62:65], v[148:151], v[186:189], v[62:65]
	v_mfma_f32_16x16x32_bf16 v[58:61], v[156:159], v[186:189], v[58:61]
	v_mfma_f32_16x16x32_bf16 v[46:49], v[148:151], v[194:197], v[46:49]
	v_mfma_f32_16x16x32_bf16 v[42:45], v[156:159], v[194:197], v[42:45]
	v_mfma_f32_16x16x32_bf16 v[30:33], v[148:151], v[202:205], v[30:33]
	v_mfma_f32_16x16x32_bf16 v[26:29], v[156:159], v[202:205], v[26:29]
	v_mfma_f32_16x16x32_bf16 v[14:17], v[148:151], v[240:243], v[14:17]
	v_mfma_f32_16x16x32_bf16 v[10:13], v[156:159], v[240:243], v[10:13]
	v_mfma_f32_16x16x32_bf16 v[54:57], v[160:163], v[182:185], v[54:57]
	v_mfma_f32_16x16x32_bf16 v[50:53], v[174:177], v[182:185], v[50:53]
	v_mfma_f32_16x16x32_bf16 v[38:41], v[160:163], v[190:193], v[38:41]
	v_mfma_f32_16x16x32_bf16 v[34:37], v[174:177], v[190:193], v[34:37]
	v_mfma_f32_16x16x32_bf16 v[22:25], v[160:163], v[198:201], v[22:25]
	v_mfma_f32_16x16x32_bf16 v[18:21], v[174:177], v[198:201], v[18:21]
	v_mfma_f32_16x16x32_bf16 v[6:9], v[160:163], v[236:239], v[6:9]
	v_mfma_f32_16x16x32_bf16 v[2:5], v[174:177], v[236:239], v[2:5]
	v_mfma_f32_16x16x32_bf16 v[54:57], v[164:167], v[186:189], v[54:57]
	v_mfma_f32_16x16x32_bf16 v[50:53], v[178:181], v[186:189], v[50:53]
	v_mfma_f32_16x16x32_bf16 v[38:41], v[164:167], v[194:197], v[38:41]
	v_mfma_f32_16x16x32_bf16 v[34:37], v[178:181], v[194:197], v[34:37]
	v_mfma_f32_16x16x32_bf16 v[22:25], v[164:167], v[202:205], v[22:25]
	v_mfma_f32_16x16x32_bf16 v[18:21], v[178:181], v[202:205], v[18:21]
	v_mfma_f32_16x16x32_bf16 v[6:9], v[164:167], v[240:243], v[6:9]
	v_mfma_f32_16x16x32_bf16 v[2:5], v[178:181], v[240:243], v[2:5]
	s_barrier
	s_add_i32 s78, s78, 2
	s_add_u32 s10, s10, 0x100
	s_addc_u32 s11, s11, 0
	s_add_u32 s49, s49, 0x100
	s_addc_u32 s77, s77, 0
	s_cmp_gt_u32 s78, 13
	s_cbranch_scc1 .Lpeel_exit_437

.Lpeel_exit_437:
	s_setprio 0
	s_and_b64 vcc, exec, s[6:7]
	s_cbranch_vccz .LBB0_440
	s_barrier

.LBB0_492:
	s_ashr_i32 s51, s50, 31
	s_lshl_b64 s[18:19], s[50:51], 19
	s_add_u32 s52, s20, s18
	s_addc_u32 s53, s39, s19
	s_and_b64 s[18:19], s[42:43], exec
	s_cselect_b32 s11, s53, s15
	s_cselect_b32 s13, s52, s14
	s_waitcnt lgkmcnt(0)
	s_ashr_i32 s49, s48, 31
	s_lshl_b64 s[18:19], s[48:49], 19
	s_add_u32 s54, s34, s18
	s_addc_u32 s55, s70, s19
	s_and_b64 s[18:19], s[42:43], exec
	s_cselect_b32 s40, s55, s17
	s_cselect_b32 s41, s54, s16
	s_add_u32 s14, s14, 0x40080
	s_addc_u32 s15, s15, 0
	s_add_u32 s44, s16, 0x100
	s_addc_u32 s45, s17, 0
	s_mov_b32 s46, -2
	v_readfirstlane_b32 s98, v208
	s_bitcmp1_b32 s98, 8
	s_cbranch_scc0 .Lsp_493
	s_setprio 1
.Lsp_493:
	s_add_u32 s16, s14, 0xfffc0080
	s_addc_u32 s17, s15, -1
	s_add_i32 s36, 0, 0x10000
	s_cmp_eq_u32 s46, 12
	s_cselect_b32 s19, s11, s17
	s_cselect_b32 s18, s13, s16
	s_cselect_b32 s17, s40, s45
	s_cselect_b32 s16, s41, s44
	s_add_i32 s37, 0, 0x14000
	v_add_u32_e32 v156, s36, v145
	v_add_u32_e32 v168, s37, v145
	ds_read_b128 v[140:143], v156
	ds_read_b128 v[148:151], v156 offset:1024
	ds_read_b128 v[152:155], v156 offset:2048
	ds_read_b128 v[156:159], v156 offset:3072
	ds_read_b128 v[160:163], v168
	ds_read_b128 v[164:167], v168 offset:1024
	ds_read_b128 v[174:177], v168 offset:2048
	ds_read_b128 v[178:181], v168 offset:3072
	v_lshl_add_u64 v[168:169], s[14:15], 0, v[136:137]
	s_add_i32 m0, s74, 0xc000
	ds_read_b128 v[182:185], v147
	ds_read_b128 v[186:189], v147 offset:1024
	ds_read_b128 v[190:193], v147 offset:2048
	ds_read_b128 v[194:197], v147 offset:3072
	ds_read_b128 v[198:201], v147 offset:4096
	ds_read_b128 v[202:205], v147 offset:5120
	ds_read_b128 v[236:239], v147 offset:6144
	ds_read_b128 v[240:243], v147 offset:7168
	global_load_lds_dwordx4 v[168:169], off
	v_lshl_add_u64 v[168:169], s[14:15], 0, v[138:139]
	s_add_i32 m0, s74, 0xe000
	s_nop 0
	global_load_lds_dwordx4 v[168:169], off
	s_waitcnt vmcnt(8)
	s_waitcnt lgkmcnt(0)
	s_barrier
	s_waitcnt lgkmcnt(0)
	v_mfma_f32_16x16x32_bf16 v[126:129], v[140:143], v[182:185], 0
	v_mfma_f32_16x16x32_bf16 v[122:125], v[152:155], v[182:185], 0
	v_mfma_f32_16x16x32_bf16 v[110:113], v[140:143], v[190:193], 0
	v_mfma_f32_16x16x32_bf16 v[106:109], v[152:155], v[190:193], 0
	v_mfma_f32_16x16x32_bf16 v[94:97], v[140:143], v[198:201], 0
	v_mfma_f32_16x16x32_bf16 v[90:93], v[152:155], v[198:201], 0
	v_mfma_f32_16x16x32_bf16 v[78:81], v[140:143], v[236:239], 0
	v_mfma_f32_16x16x32_bf16 v[74:77], v[152:155], v[236:239], 0
	v_mfma_f32_16x16x32_bf16 v[126:129], v[148:151], v[186:189], v[126:129]
	v_mfma_f32_16x16x32_bf16 v[122:125], v[156:159], v[186:189], v[122:125]
	v_mfma_f32_16x16x32_bf16 v[110:113], v[148:151], v[194:197], v[110:113]
	v_mfma_f32_16x16x32_bf16 v[106:109], v[156:159], v[194:197], v[106:109]
	v_mfma_f32_16x16x32_bf16 v[94:97], v[148:151], v[202:205], v[94:97]
	v_mfma_f32_16x16x32_bf16 v[90:93], v[156:159], v[202:205], v[90:93]
	v_mfma_f32_16x16x32_bf16 v[78:81], v[148:151], v[240:243], v[78:81]
	v_mfma_f32_16x16x32_bf16 v[74:77], v[156:159], v[240:243], v[74:77]
	v_mfma_f32_16x16x32_bf16 v[118:121], v[160:163], v[182:185], 0
	v_mfma_f32_16x16x32_bf16 v[114:117], v[174:177], v[182:185], 0
	v_mfma_f32_16x16x32_bf16 v[102:105], v[160:163], v[190:193], 0
	v_mfma_f32_16x16x32_bf16 v[98:101], v[174:177], v[190:193], 0
	v_mfma_f32_16x16x32_bf16 v[86:89], v[160:163], v[198:201], 0
	v_mfma_f32_16x16x32_bf16 v[82:85], v[174:177], v[198:201], 0
	v_mfma_f32_16x16x32_bf16 v[70:73], v[160:163], v[236:239], 0
	v_mfma_f32_16x16x32_bf16 v[66:69], v[174:177], v[236:239], 0
	v_mfma_f32_16x16x32_bf16 v[118:121], v[164:167], v[186:189], v[118:121]
	v_mfma_f32_16x16x32_bf16 v[114:117], v[178:181], v[186:189], v[114:117]
	v_mfma_f32_16x16x32_bf16 v[102:105], v[164:167], v[194:197], v[102:105]
	v_mfma_f32_16x16x32_bf16 v[98:101], v[178:181], v[194:197], v[98:101]
	v_mfma_f32_16x16x32_bf16 v[86:89], v[164:167], v[202:205], v[86:89]
	v_mfma_f32_16x16x32_bf16 v[82:85], v[178:181], v[202:205], v[82:85]
	v_mfma_f32_16x16x32_bf16 v[70:73], v[164:167], v[240:243], v[70:73]
	v_mfma_f32_16x16x32_bf16 v[66:69], v[178:181], v[240:243], v[66:69]
	s_barrier
	s_add_i32 s36, s36, s71
	v_lshl_add_u64 v[168:169], s[16:17], 0, v[0:1]
	s_mov_b32 m0, s36
	ds_read_b128 v[182:185], v147 offset:16384
	ds_read_b128 v[186:189], v147 offset:17408
	ds_read_b128 v[190:193], v147 offset:18432
	ds_read_b128 v[194:197], v147 offset:19456
	ds_read_b128 v[198:201], v147 offset:20480
	ds_read_b128 v[202:205], v147 offset:21504
	ds_read_b128 v[236:239], v147 offset:22528
	ds_read_b128 v[240:243], v147 offset:23552
	global_load_lds_dwordx4 v[168:169], off
	s_add_i32 m0, s36, 0x2000
	s_add_u32 s88, s16, 0x40000
	v_lshl_add_u64 v[206:207], s[16:17], 0, v[134:135]
	s_addc_u32 s89, s17, 0
	s_add_i32 s36, s37, s71
	global_load_lds_dwordx4 v[206:207], off
	v_lshl_add_u64 v[244:245], s[88:89], 0, v[0:1]
	s_mov_b32 m0, s36
	v_lshl_add_u64 v[246:247], s[18:19], 0, v[132:133]
	global_load_lds_dwordx4 v[244:245], off
	v_lshl_add_u64 v[244:245], s[88:89], 0, v[134:135]
	s_add_i32 m0, s36, 0x2000
	s_nop 0
	global_load_lds_dwordx4 v[244:245], off
	v_lshl_add_u64 v[244:245], s[18:19], 0, v[130:131]
	s_mov_b32 m0, s74
	s_nop 0
	global_load_lds_dwordx4 v[244:245], off
	s_mov_b32 m0, s75
	s_nop 0
	global_load_lds_dwordx4 v[246:247], off
	s_waitcnt vmcnt(8)
	s_waitcnt lgkmcnt(0)
	s_barrier
	s_waitcnt lgkmcnt(0)
	v_mfma_f32_16x16x32_bf16 v[62:65], v[140:143], v[182:185], 0
	v_mfma_f32_16x16x32_bf16 v[58:61], v[152:155], v[182:185], 0
	v_mfma_f32_16x16x32_bf16 v[46:49], v[140:143], v[190:193], 0
	v_mfma_f32_16x16x32_bf16 v[42:45], v[152:155], v[190:193], 0
	v_mfma_f32_16x16x32_bf16 v[30:33], v[140:143], v[198:201], 0
	v_mfma_f32_16x16x32_bf16 v[26:29], v[152:155], v[198:201], 0
	v_mfma_f32_16x16x32_bf16 v[14:17], v[140:143], v[236:239], 0
	v_mfma_f32_16x16x32_bf16 v[10:13], v[152:155], v[236:239], 0
	v_mfma_f32_16x16x32_bf16 v[62:65], v[148:151], v[186:189], v[62:65]
	v_mfma_f32_16x16x32_bf16 v[58:61], v[156:159], v[186:189], v[58:61]
	v_mfma_f32_16x16x32_bf16 v[46:49], v[148:151], v[194:197], v[46:49]
	v_mfma_f32_16x16x32_bf16 v[42:45], v[156:159], v[194:197], v[42:45]
	v_mfma_f32_16x16x32_bf16 v[30:33], v[148:151], v[202:205], v[30:33]
	v_mfma_f32_16x16x32_bf16 v[26:29], v[156:159], v[202:205], v[26:29]
	v_mfma_f32_16x16x32_bf16 v[14:17], v[148:151], v[240:243], v[14:17]
	v_mfma_f32_16x16x32_bf16 v[10:13], v[156:159], v[240:243], v[10:13]
	v_mfma_f32_16x16x32_bf16 v[54:57], v[160:163], v[182:185], 0
	v_mfma_f32_16x16x32_bf16 v[50:53], v[174:177], v[182:185], 0
	v_mfma_f32_16x16x32_bf16 v[38:41], v[160:163], v[190:193], 0
	v_mfma_f32_16x16x32_bf16 v[34:37], v[174:177], v[190:193], 0
	v_mfma_f32_16x16x32_bf16 v[22:25], v[160:163], v[198:201], 0
	v_mfma_f32_16x16x32_bf16 v[18:21], v[174:177], v[198:201], 0
	v_mfma_f32_16x16x32_bf16 v[6:9], v[160:163], v[236:239], 0
	v_mfma_f32_16x16x32_bf16 v[2:5], v[174:177], v[236:239], 0
	v_mfma_f32_16x16x32_bf16 v[54:57], v[164:167], v[186:189], v[54:57]
	v_mfma_f32_16x16x32_bf16 v[50:53], v[178:181], v[186:189], v[50:53]
	v_mfma_f32_16x16x32_bf16 v[38:41], v[164:167], v[194:197], v[38:41]
	v_mfma_f32_16x16x32_bf16 v[34:37], v[178:181], v[194:197], v[34:37]
	v_mfma_f32_16x16x32_bf16 v[22:25], v[164:167], v[202:205], v[22:25]
	v_mfma_f32_16x16x32_bf16 v[18:21], v[178:181], v[202:205], v[18:21]
	v_mfma_f32_16x16x32_bf16 v[6:9], v[164:167], v[240:243], v[6:9]
	v_mfma_f32_16x16x32_bf16 v[2:5], v[178:181], v[240:243], v[2:5]
	s_barrier
	s_add_i32 s36, 0, 0x18000
	s_add_i32 s37, 0, 0x1c000
	v_add_u32_e32 v156, s36, v145
	v_add_u32_e32 v178, s37, v145
	ds_read_b128 v[140:143], v156
	ds_read_b128 v[148:151], v156 offset:1024
	ds_read_b128 v[152:155], v156 offset:2048
	ds_read_b128 v[156:159], v156 offset:3072
	ds_read_b128 v[160:163], v178
	ds_read_b128 v[164:167], v178 offset:1024
	ds_read_b128 v[174:177], v178 offset:2048
	ds_read_b128 v[178:181], v178 offset:3072
	s_add_u32 s18, s18, 0x40000
	s_addc_u32 s19, s19, 0
	s_mov_b32 m0, s77
	v_lshl_add_u64 v[248:249], s[18:19], 0, v[130:131]
	ds_read_b128 v[182:185], v147 offset:32768
	ds_read_b128 v[186:189], v147 offset:33792
	ds_read_b128 v[190:193], v147 offset:34816
	ds_read_b128 v[194:197], v147 offset:35840
	ds_read_b128 v[198:201], v147 offset:36864
	ds_read_b128 v[202:205], v147 offset:37888
	ds_read_b128 v[236:239], v147 offset:38912
	ds_read_b128 v[240:243], v147 offset:39936
	global_load_lds_dwordx4 v[248:249], off
	v_lshl_add_u64 v[248:249], s[18:19], 0, v[132:133]
	s_mov_b32 m0, s78
	s_nop 0
	global_load_lds_dwordx4 v[248:249], off
	s_waitcnt vmcnt(8)
	s_waitcnt lgkmcnt(0)
	s_barrier
	s_waitcnt lgkmcnt(0)
	v_mfma_f32_16x16x32_bf16 v[126:129], v[140:143], v[182:185], v[126:129]
	v_mfma_f32_16x16x32_bf16 v[122:125], v[152:155], v[182:185], v[122:125]
	v_mfma_f32_16x16x32_bf16 v[110:113], v[140:143], v[190:193], v[110:113]
	v_mfma_f32_16x16x32_bf16 v[106:109], v[152:155], v[190:193], v[106:109]
	v_mfma_f32_16x16x32_bf16 v[94:97], v[140:143], v[198:201], v[94:97]
	v_mfma_f32_16x16x32_bf16 v[90:93], v[152:155], v[198:201], v[90:93]
	v_mfma_f32_16x16x32_bf16 v[78:81], v[140:143], v[236:239], v[78:81]
	v_mfma_f32_16x16x32_bf16 v[74:77], v[152:155], v[236:239], v[74:77]
	v_mfma_f32_16x16x32_bf16 v[126:129], v[148:151], v[186:189], v[126:129]
	v_mfma_f32_16x16x32_bf16 v[122:125], v[156:159], v[186:189], v[122:125]
	v_mfma_f32_16x16x32_bf16 v[110:113], v[148:151], v[194:197], v[110:113]
	v_mfma_f32_16x16x32_bf16 v[106:109], v[156:159], v[194:197], v[106:109]
	v_mfma_f32_16x16x32_bf16 v[94:97], v[148:151], v[202:205], v[94:97]
	v_mfma_f32_16x16x32_bf16 v[90:93], v[156:159], v[202:205], v[90:93]
	v_mfma_f32_16x16x32_bf16 v[78:81], v[148:151], v[240:243], v[78:81]
	v_mfma_f32_16x16x32_bf16 v[74:77], v[156:159], v[240:243], v[74:77]
	v_mfma_f32_16x16x32_bf16 v[118:121], v[160:163], v[182:185], v[118:121]
	v_mfma_f32_16x16x32_bf16 v[114:117], v[174:177], v[182:185], v[114:117]
	v_mfma_f32_16x16x32_bf16 v[102:105], v[160:163], v[190:193], v[102:105]
	v_mfma_f32_16x16x32_bf16 v[98:101], v[174:177], v[190:193], v[98:101]
	v_mfma_f32_16x16x32_bf16 v[86:89], v[160:163], v[198:201], v[86:89]
	v_mfma_f32_16x16x32_bf16 v[82:85], v[174:177], v[198:201], v[82:85]
	v_mfma_f32_16x16x32_bf16 v[70:73], v[160:163], v[236:239], v[70:73]
	v_mfma_f32_16x16x32_bf16 v[66:69], v[174:177], v[236:239], v[66:69]
	v_mfma_f32_16x16x32_bf16 v[118:121], v[164:167], v[186:189], v[118:121]
	v_mfma_f32_16x16x32_bf16 v[114:117], v[178:181], v[186:189], v[114:117]
	v_mfma_f32_16x16x32_bf16 v[102:105], v[164:167], v[194:197], v[102:105]
	v_mfma_f32_16x16x32_bf16 v[98:101], v[178:181], v[194:197], v[98:101]
	v_mfma_f32_16x16x32_bf16 v[86:89], v[164:167], v[202:205], v[86:89]
	v_mfma_f32_16x16x32_bf16 v[82:85], v[178:181], v[202:205], v[82:85]
	v_mfma_f32_16x16x32_bf16 v[70:73], v[164:167], v[240:243], v[70:73]
	v_mfma_f32_16x16x32_bf16 v[66:69], v[178:181], v[240:243], v[66:69]
	s_barrier
	s_add_i32 s18, s36, s71
	v_lshl_add_u64 v[168:169], v[168:169], 0, s[4:5]
	s_mov_b32 m0, s18
	ds_read_b128 v[182:185], v147 offset:49152
	ds_read_b128 v[186:189], v147 offset:50176
	ds_read_b128 v[190:193], v147 offset:51200
	ds_read_b128 v[194:197], v147 offset:52224
	ds_read_b128 v[198:201], v147 offset:53248
	ds_read_b128 v[202:205], v147 offset:54272
	ds_read_b128 v[236:239], v147 offset:55296
	ds_read_b128 v[240:243], v147 offset:56320
	global_load_lds_dwordx4 v[168:169], off
	s_add_i32 m0, s18, 0x2000
	s_add_u32 s16, s16, 0x40080
	v_lshl_add_u64 v[168:169], v[206:207], 0, s[4:5]
	s_addc_u32 s17, s17, 0
	s_add_i32 s18, s37, s71
	global_load_lds_dwordx4 v[168:169], off
	v_lshl_add_u64 v[168:169], s[16:17], 0, v[0:1]
	s_mov_b32 m0, s18
	s_nop 0
	global_load_lds_dwordx4 v[168:169], off
	v_lshl_add_u64 v[168:169], s[16:17], 0, v[134:135]
	s_add_i32 m0, s18, 0x2000
	s_nop 0
	global_load_lds_dwordx4 v[168:169], off
	v_lshl_add_u64 v[168:169], v[244:245], 0, s[4:5]
	s_mov_b32 m0, s79
	s_nop 0
	global_load_lds_dwordx4 v[168:169], off
	v_lshl_add_u64 v[168:169], v[246:247], 0, s[4:5]
	s_mov_b32 m0, s82
	s_nop 0
	global_load_lds_dwordx4 v[168:169], off
	s_waitcnt vmcnt(8)
	s_waitcnt lgkmcnt(0)
	s_barrier
	s_waitcnt lgkmcnt(0)
	v_mfma_f32_16x16x32_bf16 v[62:65], v[140:143], v[182:185], v[62:65]
	v_mfma_f32_16x16x32_bf16 v[58:61], v[152:155], v[182:185], v[58:61]
	v_mfma_f32_16x16x32_bf16 v[46:49], v[140:143], v[190:193], v[46:49]
	v_mfma_f32_16x16x32_bf16 v[42:45], v[152:155], v[190:193], v[42:45]
	v_mfma_f32_16x16x32_bf16 v[30:33], v[140:143], v[198:201], v[30:33]
	v_mfma_f32_16x16x32_bf16 v[26:29], v[152:155], v[198:201], v[26:29]
	v_mfma_f32_16x16x32_bf16 v[14:17], v[140:143], v[236:239], v[14:17]
	v_mfma_f32_16x16x32_bf16 v[10:13], v[152:155], v[236:239], v[10:13]
	v_mfma_f32_16x16x32_bf16 v[62:65], v[148:151], v[186:189], v[62:65]
	v_mfma_f32_16x16x32_bf16 v[58:61], v[156:159], v[186:189], v[58:61]
	v_mfma_f32_16x16x32_bf16 v[46:49], v[148:151], v[194:197], v[46:49]
	v_mfma_f32_16x16x32_bf16 v[42:45], v[156:159], v[194:197], v[42:45]
	v_mfma_f32_16x16x32_bf16 v[30:33], v[148:151], v[202:205], v[30:33]
	v_mfma_f32_16x16x32_bf16 v[26:29], v[156:159], v[202:205], v[26:29]
	v_mfma_f32_16x16x32_bf16 v[14:17], v[148:151], v[240:243], v[14:17]
	v_mfma_f32_16x16x32_bf16 v[10:13], v[156:159], v[240:243], v[10:13]
	v_mfma_f32_16x16x32_bf16 v[54:57], v[160:163], v[182:185], v[54:57]
	v_mfma_f32_16x16x32_bf16 v[50:53], v[174:177], v[182:185], v[50:53]
	v_mfma_f32_16x16x32_bf16 v[38:41], v[160:163], v[190:193], v[38:41]
	v_mfma_f32_16x16x32_bf16 v[34:37], v[174:177], v[190:193], v[34:37]
	v_mfma_f32_16x16x32_bf16 v[22:25], v[160:163], v[198:201], v[22:25]
	v_mfma_f32_16x16x32_bf16 v[18:21], v[174:177], v[198:201], v[18:21]
	v_mfma_f32_16x16x32_bf16 v[6:9], v[160:163], v[236:239], v[6:9]
	v_mfma_f32_16x16x32_bf16 v[2:5], v[174:177], v[236:239], v[2:5]
	v_mfma_f32_16x16x32_bf16 v[54:57], v[164:167], v[186:189], v[54:57]
	v_mfma_f32_16x16x32_bf16 v[50:53], v[178:181], v[186:189], v[50:53]
	v_mfma_f32_16x16x32_bf16 v[38:41], v[164:167], v[194:197], v[38:41]
	v_mfma_f32_16x16x32_bf16 v[34:37], v[178:181], v[194:197], v[34:37]
	v_mfma_f32_16x16x32_bf16 v[22:25], v[164:167], v[202:205], v[22:25]
	v_mfma_f32_16x16x32_bf16 v[18:21], v[178:181], v[202:205], v[18:21]
	v_mfma_f32_16x16x32_bf16 v[6:9], v[164:167], v[240:243], v[6:9]
	v_mfma_f32_16x16x32_bf16 v[2:5], v[178:181], v[240:243], v[2:5]
	s_barrier
	s_add_i32 s46, s46, 2
	s_add_u32 s14, s14, 0x100
	s_addc_u32 s15, s15, 0
	s_add_u32 s44, s44, 0x100
	s_addc_u32 s45, s45, 0
	s_cmp_gt_u32 s46, 13
	s_cbranch_scc1 .Lpeel_exit_493
